# K-loops: LDS-DMA loads issued before the fragment ds_reads in every load segment (dependency-checked reorder)
# baseline (speedup 1.0000x reference)
.LBB0_137:
	s_add_u32 s10, s4, 0xfff80080
	s_addc_u32 s11, s5, -1
	s_cmp_eq_u32 s78, 28
	s_cselect_b32 s67, s7, s11
	s_cselect_b32 s66, s9, s10
	s_cselect_b32 s11, s36, s77
	s_cselect_b32 s10, s73, s76
	v_lshl_add_u64 v[196:197], s[4:5], 0, v[144:145]
	s_add_i32 m0, s86, 0xc000
	s_nop 0
	global_load_lds_dwordx4 v[196:197], off
	v_lshl_add_u64 v[196:197], s[4:5], 0, v[146:147]
	s_add_i32 m0, s86, 0xe000
	s_nop 0
	global_load_lds_dwordx4 v[196:197], off
	ds_read_b128 v[128:131], v172
	ds_read_b128 v[152:155], v172 offset:1024
	ds_read_b128 v[156:159], v172 offset:2048
	ds_read_b128 v[160:163], v172 offset:3072
	ds_read_b128 v[182:185], v173
	ds_read_b128 v[188:191], v173 offset:1024
	ds_read_b128 v[192:195], v173 offset:2048
	ds_read_b128 v[204:207], v173 offset:3072
	ds_read_b128 v[208:211], v174
	ds_read_b128 v[212:215], v174 offset:1024
	ds_read_b128 v[216:219], v174 offset:2048
	ds_read_b128 v[222:225], v174 offset:3072
	ds_read_b128 v[226:229], v174 offset:4096
	ds_read_b128 v[230:233], v174 offset:5120
	ds_read_b128 v[234:237], v174 offset:6144
	ds_read_b128 v[238:241], v174 offset:7168
	s_waitcnt vmcnt(8)
	s_waitcnt lgkmcnt(0)
	s_barrier
	s_setprio 1
	s_waitcnt lgkmcnt(0)
	v_mfma_f32_16x16x32_bf16 v[124:127], v[128:131], v[208:211], v[124:127]
	v_mfma_f32_16x16x32_bf16 v[120:123], v[156:159], v[208:211], v[120:123]
	v_mfma_f32_16x16x32_bf16 v[108:111], v[128:131], v[216:219], v[108:111]
	v_mfma_f32_16x16x32_bf16 v[104:107], v[156:159], v[216:219], v[104:107]
	v_mfma_f32_16x16x32_bf16 v[92:95], v[128:131], v[226:229], v[92:95]
	v_mfma_f32_16x16x32_bf16 v[88:91], v[156:159], v[226:229], v[88:91]
	v_mfma_f32_16x16x32_bf16 v[76:79], v[128:131], v[234:237], v[76:79]
	v_mfma_f32_16x16x32_bf16 v[72:75], v[156:159], v[234:237], v[72:75]
	v_mfma_f32_16x16x32_bf16 v[124:127], v[152:155], v[212:215], v[124:127]
	v_mfma_f32_16x16x32_bf16 v[120:123], v[160:163], v[212:215], v[120:123]
	v_mfma_f32_16x16x32_bf16 v[108:111], v[152:155], v[222:225], v[108:111]
	v_mfma_f32_16x16x32_bf16 v[104:107], v[160:163], v[222:225], v[104:107]
	v_mfma_f32_16x16x32_bf16 v[92:95], v[152:155], v[230:233], v[92:95]
	v_mfma_f32_16x16x32_bf16 v[88:91], v[160:163], v[230:233], v[88:91]
	v_mfma_f32_16x16x32_bf16 v[76:79], v[152:155], v[238:241], v[76:79]
	v_mfma_f32_16x16x32_bf16 v[72:75], v[160:163], v[238:241], v[72:75]
	s_setprio 0
	s_setprio 1
	v_mfma_f32_16x16x32_bf16 v[116:119], v[182:185], v[208:211], v[116:119]
	v_mfma_f32_16x16x32_bf16 v[112:115], v[192:195], v[208:211], v[112:115]
	v_mfma_f32_16x16x32_bf16 v[100:103], v[182:185], v[216:219], v[100:103]
	v_mfma_f32_16x16x32_bf16 v[96:99], v[192:195], v[216:219], v[96:99]
	v_mfma_f32_16x16x32_bf16 v[84:87], v[182:185], v[226:229], v[84:87]
	v_mfma_f32_16x16x32_bf16 v[80:83], v[192:195], v[226:229], v[80:83]
	v_mfma_f32_16x16x32_bf16 v[68:71], v[182:185], v[234:237], v[68:71]
	v_mfma_f32_16x16x32_bf16 v[64:67], v[192:195], v[234:237], v[64:67]
	v_mfma_f32_16x16x32_bf16 v[116:119], v[188:191], v[212:215], v[116:119]
	v_mfma_f32_16x16x32_bf16 v[112:115], v[204:207], v[212:215], v[112:115]
	v_mfma_f32_16x16x32_bf16 v[100:103], v[188:191], v[222:225], v[100:103]
	v_mfma_f32_16x16x32_bf16 v[96:99], v[204:207], v[222:225], v[96:99]
	v_mfma_f32_16x16x32_bf16 v[84:87], v[188:191], v[230:233], v[84:87]
	v_mfma_f32_16x16x32_bf16 v[80:83], v[204:207], v[230:233], v[80:83]
	v_mfma_f32_16x16x32_bf16 v[68:71], v[188:191], v[238:241], v[68:71]
	v_mfma_f32_16x16x32_bf16 v[64:67], v[204:207], v[238:241], v[64:67]
	s_setprio 0
	s_barrier
	s_add_i32 s34, s53, s81
	v_lshl_add_u64 v[196:197], s[10:11], 0, v[134:135]
	s_mov_b32 m0, s34
	s_nop 0
	global_load_lds_dwordx4 v[196:197], off
	s_add_i32 m0, s34, 0x2000
	s_add_u32 s34, s10, 0x80000
	v_lshl_add_u64 v[242:243], s[10:11], 0, v[138:139]
	s_addc_u32 s35, s11, 0
	s_add_i32 s79, s19, s81
	global_load_lds_dwordx4 v[242:243], off
	v_lshl_add_u64 v[244:245], s[34:35], 0, v[134:135]
	s_mov_b32 m0, s79
	v_lshl_add_u64 v[246:247], s[66:67], 0, v[136:137]
	global_load_lds_dwordx4 v[244:245], off
	v_lshl_add_u64 v[244:245], s[34:35], 0, v[138:139]
	s_add_i32 m0, s79, 0x2000
	s_nop 0
	global_load_lds_dwordx4 v[244:245], off
	v_lshl_add_u64 v[244:245], s[66:67], 0, v[132:133]
	s_mov_b32 m0, s86
	s_nop 0
	global_load_lds_dwordx4 v[244:245], off
	s_mov_b32 m0, s87
	s_nop 0
	global_load_lds_dwordx4 v[246:247], off
	ds_read_b128 v[208:211], v174 offset:16384
	ds_read_b128 v[212:215], v174 offset:17408
	ds_read_b128 v[216:219], v174 offset:18432
	ds_read_b128 v[222:225], v174 offset:19456
	ds_read_b128 v[226:229], v174 offset:20480
	ds_read_b128 v[230:233], v174 offset:21504
	ds_read_b128 v[234:237], v174 offset:22528
	ds_read_b128 v[238:241], v174 offset:23552
	s_waitcnt vmcnt(8)
	s_waitcnt lgkmcnt(0)
	s_barrier
	s_setprio 1
	s_waitcnt lgkmcnt(0)
	v_mfma_f32_16x16x32_bf16 v[60:63], v[128:131], v[208:211], v[60:63]
	v_mfma_f32_16x16x32_bf16 v[56:59], v[156:159], v[208:211], v[56:59]
	v_mfma_f32_16x16x32_bf16 v[44:47], v[128:131], v[216:219], v[44:47]
	v_mfma_f32_16x16x32_bf16 v[40:43], v[156:159], v[216:219], v[40:43]
	v_mfma_f32_16x16x32_bf16 v[28:31], v[128:131], v[226:229], v[28:31]
	v_mfma_f32_16x16x32_bf16 v[24:27], v[156:159], v[226:229], v[24:27]
	v_mfma_f32_16x16x32_bf16 v[12:15], v[128:131], v[234:237], v[12:15]
	v_mfma_f32_16x16x32_bf16 v[8:11], v[156:159], v[234:237], v[8:11]
	v_mfma_f32_16x16x32_bf16 v[60:63], v[152:155], v[212:215], v[60:63]
	v_mfma_f32_16x16x32_bf16 v[56:59], v[160:163], v[212:215], v[56:59]
	v_mfma_f32_16x16x32_bf16 v[44:47], v[152:155], v[222:225], v[44:47]
	v_mfma_f32_16x16x32_bf16 v[40:43], v[160:163], v[222:225], v[40:43]
	v_mfma_f32_16x16x32_bf16 v[28:31], v[152:155], v[230:233], v[28:31]
	v_mfma_f32_16x16x32_bf16 v[24:27], v[160:163], v[230:233], v[24:27]
	v_mfma_f32_16x16x32_bf16 v[12:15], v[152:155], v[238:241], v[12:15]
	v_mfma_f32_16x16x32_bf16 v[8:11], v[160:163], v[238:241], v[8:11]
	s_setprio 0
	s_setprio 1
	v_mfma_f32_16x16x32_bf16 v[52:55], v[182:185], v[208:211], v[52:55]
	v_mfma_f32_16x16x32_bf16 v[48:51], v[192:195], v[208:211], v[48:51]
	v_mfma_f32_16x16x32_bf16 v[36:39], v[182:185], v[216:219], v[36:39]
	v_mfma_f32_16x16x32_bf16 v[32:35], v[192:195], v[216:219], v[32:35]
	v_mfma_f32_16x16x32_bf16 v[20:23], v[182:185], v[226:229], v[20:23]
	v_mfma_f32_16x16x32_bf16 v[16:19], v[192:195], v[226:229], v[16:19]
	v_mfma_f32_16x16x32_bf16 v[4:7], v[182:185], v[234:237], v[4:7]
	v_mfma_f32_16x16x32_bf16 v[0:3], v[192:195], v[234:237], v[0:3]
	v_mfma_f32_16x16x32_bf16 v[52:55], v[188:191], v[212:215], v[52:55]
	v_mfma_f32_16x16x32_bf16 v[48:51], v[204:207], v[212:215], v[48:51]
	v_mfma_f32_16x16x32_bf16 v[36:39], v[188:191], v[222:225], v[36:39]
	v_mfma_f32_16x16x32_bf16 v[32:35], v[204:207], v[222:225], v[32:35]
	v_mfma_f32_16x16x32_bf16 v[20:23], v[188:191], v[230:233], v[20:23]
	v_mfma_f32_16x16x32_bf16 v[16:19], v[204:207], v[230:233], v[16:19]
	v_mfma_f32_16x16x32_bf16 v[4:7], v[188:191], v[238:241], v[4:7]
	v_mfma_f32_16x16x32_bf16 v[0:3], v[204:207], v[238:241], v[0:3]
	s_setprio 0
	s_barrier
	s_add_i32 s79, 0, 0x18000
	s_add_i32 s84, 0, 0x1c000
	s_add_u32 s34, s66, 0x80000
	s_addc_u32 s35, s67, 0
	s_mov_b32 m0, s88
	v_lshl_add_u64 v[248:249], s[34:35], 0, v[132:133]
	global_load_lds_dwordx4 v[248:249], off
	v_lshl_add_u64 v[248:249], s[34:35], 0, v[136:137]
	s_mov_b32 m0, s89
	s_nop 0
	global_load_lds_dwordx4 v[248:249], off
	v_add_u32_e32 v140, s79, v164
	ds_read_b128 v[128:131], v140
	ds_read_b128 v[152:155], v140 offset:1024
	ds_read_b128 v[156:159], v140 offset:2048
	ds_read_b128 v[160:163], v140 offset:3072
	v_add_u32_e32 v140, s84, v164
	ds_read_b128 v[182:185], v140
	ds_read_b128 v[188:191], v140 offset:1024
	ds_read_b128 v[192:195], v140 offset:2048
	ds_read_b128 v[204:207], v140 offset:3072
	ds_read_b128 v[208:211], v174 offset:32768
	ds_read_b128 v[212:215], v174 offset:33792
	ds_read_b128 v[216:219], v174 offset:34816
	ds_read_b128 v[222:225], v174 offset:35840
	ds_read_b128 v[226:229], v174 offset:36864
	ds_read_b128 v[230:233], v174 offset:37888
	ds_read_b128 v[234:237], v174 offset:38912
	ds_read_b128 v[238:241], v174 offset:39936
	s_waitcnt vmcnt(8)
	s_waitcnt lgkmcnt(0)
	s_barrier
	s_setprio 1
	s_waitcnt lgkmcnt(0)
	v_mfma_f32_16x16x32_bf16 v[124:127], v[128:131], v[208:211], v[124:127]
	v_mfma_f32_16x16x32_bf16 v[120:123], v[156:159], v[208:211], v[120:123]
	v_mfma_f32_16x16x32_bf16 v[108:111], v[128:131], v[216:219], v[108:111]
	v_mfma_f32_16x16x32_bf16 v[104:107], v[156:159], v[216:219], v[104:107]
	v_mfma_f32_16x16x32_bf16 v[92:95], v[128:131], v[226:229], v[92:95]
	v_mfma_f32_16x16x32_bf16 v[88:91], v[156:159], v[226:229], v[88:91]
	v_mfma_f32_16x16x32_bf16 v[76:79], v[128:131], v[234:237], v[76:79]
	v_mfma_f32_16x16x32_bf16 v[72:75], v[156:159], v[234:237], v[72:75]
	v_mfma_f32_16x16x32_bf16 v[124:127], v[152:155], v[212:215], v[124:127]
	v_mfma_f32_16x16x32_bf16 v[120:123], v[160:163], v[212:215], v[120:123]
	v_mfma_f32_16x16x32_bf16 v[108:111], v[152:155], v[222:225], v[108:111]
	v_mfma_f32_16x16x32_bf16 v[104:107], v[160:163], v[222:225], v[104:107]
	v_mfma_f32_16x16x32_bf16 v[92:95], v[152:155], v[230:233], v[92:95]
	v_mfma_f32_16x16x32_bf16 v[88:91], v[160:163], v[230:233], v[88:91]
	v_mfma_f32_16x16x32_bf16 v[76:79], v[152:155], v[238:241], v[76:79]
	v_mfma_f32_16x16x32_bf16 v[72:75], v[160:163], v[238:241], v[72:75]
	s_setprio 0
	s_setprio 1
	v_mfma_f32_16x16x32_bf16 v[116:119], v[182:185], v[208:211], v[116:119]
	v_mfma_f32_16x16x32_bf16 v[112:115], v[192:195], v[208:211], v[112:115]
	v_mfma_f32_16x16x32_bf16 v[100:103], v[182:185], v[216:219], v[100:103]
	v_mfma_f32_16x16x32_bf16 v[96:99], v[192:195], v[216:219], v[96:99]
	v_mfma_f32_16x16x32_bf16 v[84:87], v[182:185], v[226:229], v[84:87]
	v_mfma_f32_16x16x32_bf16 v[80:83], v[192:195], v[226:229], v[80:83]
	v_mfma_f32_16x16x32_bf16 v[68:71], v[182:185], v[234:237], v[68:71]
	v_mfma_f32_16x16x32_bf16 v[64:67], v[192:195], v[234:237], v[64:67]
	v_mfma_f32_16x16x32_bf16 v[116:119], v[188:191], v[212:215], v[116:119]
	v_mfma_f32_16x16x32_bf16 v[112:115], v[204:207], v[212:215], v[112:115]
	v_mfma_f32_16x16x32_bf16 v[100:103], v[188:191], v[222:225], v[100:103]
	v_mfma_f32_16x16x32_bf16 v[96:99], v[204:207], v[222:225], v[96:99]
	v_mfma_f32_16x16x32_bf16 v[84:87], v[188:191], v[230:233], v[84:87]
	v_mfma_f32_16x16x32_bf16 v[80:83], v[204:207], v[230:233], v[80:83]
	v_mfma_f32_16x16x32_bf16 v[68:71], v[188:191], v[238:241], v[68:71]
	v_mfma_f32_16x16x32_bf16 v[64:67], v[204:207], v[238:241], v[64:67]
	s_setprio 0
	s_barrier
	s_add_i32 s34, s79, s81
	v_lshl_add_u64 v[196:197], v[196:197], 0, s[50:51]
	s_mov_b32 m0, s34
	s_nop 0
	global_load_lds_dwordx4 v[196:197], off
	s_add_i32 m0, s34, 0x2000
	s_add_u32 s10, s10, 0x80080
	v_lshl_add_u64 v[196:197], v[242:243], 0, s[50:51]
	s_addc_u32 s11, s11, 0
	s_add_i32 s34, s84, s81
	global_load_lds_dwordx4 v[196:197], off
	v_lshl_add_u64 v[196:197], s[10:11], 0, v[134:135]
	s_mov_b32 m0, s34
	s_nop 0
	global_load_lds_dwordx4 v[196:197], off
	v_lshl_add_u64 v[196:197], s[10:11], 0, v[138:139]
	s_add_i32 m0, s34, 0x2000
	s_nop 0
	global_load_lds_dwordx4 v[196:197], off
	v_lshl_add_u64 v[196:197], v[244:245], 0, s[50:51]
	s_mov_b32 m0, s40
	s_nop 0
	global_load_lds_dwordx4 v[196:197], off
	v_lshl_add_u64 v[196:197], v[246:247], 0, s[50:51]
	s_mov_b32 m0, s41
	s_nop 0
	global_load_lds_dwordx4 v[196:197], off
	ds_read_b128 v[208:211], v174 offset:49152
	ds_read_b128 v[212:215], v174 offset:50176
	ds_read_b128 v[216:219], v174 offset:51200
	ds_read_b128 v[222:225], v174 offset:52224
	ds_read_b128 v[226:229], v174 offset:53248
	ds_read_b128 v[230:233], v174 offset:54272
	ds_read_b128 v[234:237], v174 offset:55296
	ds_read_b128 v[238:241], v174 offset:56320
	s_waitcnt vmcnt(8)
	s_waitcnt lgkmcnt(0)
	s_barrier
	s_setprio 1
	s_waitcnt lgkmcnt(0)
	v_mfma_f32_16x16x32_bf16 v[60:63], v[128:131], v[208:211], v[60:63]
	v_mfma_f32_16x16x32_bf16 v[56:59], v[156:159], v[208:211], v[56:59]
	v_mfma_f32_16x16x32_bf16 v[44:47], v[128:131], v[216:219], v[44:47]
	v_mfma_f32_16x16x32_bf16 v[40:43], v[156:159], v[216:219], v[40:43]
	v_mfma_f32_16x16x32_bf16 v[28:31], v[128:131], v[226:229], v[28:31]
	v_mfma_f32_16x16x32_bf16 v[24:27], v[156:159], v[226:229], v[24:27]
	v_mfma_f32_16x16x32_bf16 v[12:15], v[128:131], v[234:237], v[12:15]
	v_mfma_f32_16x16x32_bf16 v[8:11], v[156:159], v[234:237], v[8:11]
	v_mfma_f32_16x16x32_bf16 v[60:63], v[152:155], v[212:215], v[60:63]
	v_mfma_f32_16x16x32_bf16 v[56:59], v[160:163], v[212:215], v[56:59]
	v_mfma_f32_16x16x32_bf16 v[44:47], v[152:155], v[222:225], v[44:47]
	v_mfma_f32_16x16x32_bf16 v[40:43], v[160:163], v[222:225], v[40:43]
	v_mfma_f32_16x16x32_bf16 v[28:31], v[152:155], v[230:233], v[28:31]
	v_mfma_f32_16x16x32_bf16 v[24:27], v[160:163], v[230:233], v[24:27]
	v_mfma_f32_16x16x32_bf16 v[12:15], v[152:155], v[238:241], v[12:15]
	v_mfma_f32_16x16x32_bf16 v[8:11], v[160:163], v[238:241], v[8:11]
	s_setprio 0
	s_setprio 1
	v_mfma_f32_16x16x32_bf16 v[52:55], v[182:185], v[208:211], v[52:55]
	v_mfma_f32_16x16x32_bf16 v[48:51], v[192:195], v[208:211], v[48:51]
	v_mfma_f32_16x16x32_bf16 v[36:39], v[182:185], v[216:219], v[36:39]
	v_mfma_f32_16x16x32_bf16 v[32:35], v[192:195], v[216:219], v[32:35]
	v_mfma_f32_16x16x32_bf16 v[20:23], v[182:185], v[226:229], v[20:23]
	v_mfma_f32_16x16x32_bf16 v[16:19], v[192:195], v[226:229], v[16:19]
	v_mfma_f32_16x16x32_bf16 v[4:7], v[182:185], v[234:237], v[4:7]
	v_mfma_f32_16x16x32_bf16 v[0:3], v[192:195], v[234:237], v[0:3]
	v_mfma_f32_16x16x32_bf16 v[52:55], v[188:191], v[212:215], v[52:55]
	v_mfma_f32_16x16x32_bf16 v[48:51], v[204:207], v[212:215], v[48:51]
	v_mfma_f32_16x16x32_bf16 v[36:39], v[188:191], v[222:225], v[36:39]
	v_mfma_f32_16x16x32_bf16 v[32:35], v[204:207], v[222:225], v[32:35]
	v_mfma_f32_16x16x32_bf16 v[20:23], v[188:191], v[230:233], v[20:23]
	v_mfma_f32_16x16x32_bf16 v[16:19], v[204:207], v[230:233], v[16:19]
	v_mfma_f32_16x16x32_bf16 v[4:7], v[188:191], v[238:241], v[4:7]
	v_mfma_f32_16x16x32_bf16 v[0:3], v[204:207], v[238:241], v[0:3]
	s_setprio 0
	s_barrier
	s_add_i32 s78, s78, 2
	s_add_u32 s4, s4, 0x100
	s_addc_u32 s5, s5, 0
	s_add_u32 s76, s76, 0x100
	s_addc_u32 s77, s77, 0
	s_cmp_gt_u32 s78, 29
	s_cbranch_scc0 .LBB0_137
	v_readlane_b32 s4, v250, 24
	v_readlane_b32 s5, v250, 25
	s_and_b64 vcc, exec, s[4:5]
	s_cbranch_vccz .LBB0_140
	s_barrier

.LBB0_701:
	s_mov_b32 m0, s66
	v_lshl_add_u64 v[138:139], s[0:1], 0, v[128:129]
	global_load_lds_dwordx4 v[138:139], off
	v_lshl_add_u64 v[138:139], s[0:1], 0, v[132:133]
	s_mov_b32 m0, s67
	s_nop 0
	global_load_lds_dwordx4 v[138:139], off
	ds_read_b128 v[148:151], v144
	ds_read_b128 v[152:155], v144 offset:1024
	ds_read_b128 v[156:159], v144 offset:2048
	ds_read_b128 v[160:163], v144 offset:3072
	ds_read_b128 v[164:167], v145
	ds_read_b128 v[168:171], v145 offset:1024
	ds_read_b128 v[172:175], v145 offset:2048
	ds_read_b128 v[180:183], v145 offset:3072
	s_add_u32 s34, s0, 0xfff80080
	s_addc_u32 s35, s1, -1
	s_cmp_eq_u32 s57, 12
	s_cselect_b32 s55, s79, s35
	s_cselect_b32 s54, s11, s34
	s_cselect_b32 s49, s63, s56
	s_cselect_b32 s48, s62, s9
	ds_read_b128 v[184:187], v146
	ds_read_b128 v[188:191], v146 offset:1024
	ds_read_b128 v[192:195], v146 offset:2048
	ds_read_b128 v[196:199], v146 offset:3072
	ds_read_b128 v[200:203], v146 offset:4096
	ds_read_b128 v[204:207], v146 offset:5120
	ds_read_b128 v[208:211], v146 offset:6144
	ds_read_b128 v[212:215], v146 offset:7168
	s_waitcnt vmcnt(8)
	s_waitcnt lgkmcnt(0)
	s_barrier
	s_setprio 1
	s_waitcnt lgkmcnt(0)
	v_mfma_f32_16x16x32_bf16 v[8:11], v[148:151], v[184:187], v[8:11]
	v_mfma_f32_16x16x32_bf16 v[12:15], v[156:159], v[184:187], v[12:15]
	v_mfma_f32_16x16x32_bf16 v[40:43], v[148:151], v[192:195], v[40:43]
	v_mfma_f32_16x16x32_bf16 v[44:47], v[156:159], v[192:195], v[44:47]
	v_mfma_f32_16x16x32_bf16 v[64:67], v[148:151], v[200:203], v[64:67]
	v_mfma_f32_16x16x32_bf16 v[68:71], v[156:159], v[200:203], v[68:71]
	v_mfma_f32_16x16x32_bf16 v[88:91], v[148:151], v[208:211], v[88:91]
	v_mfma_f32_16x16x32_bf16 v[92:95], v[156:159], v[208:211], v[92:95]
	v_mfma_f32_16x16x32_bf16 v[8:11], v[152:155], v[188:191], v[8:11]
	v_mfma_f32_16x16x32_bf16 v[12:15], v[160:163], v[188:191], v[12:15]
	v_mfma_f32_16x16x32_bf16 v[40:43], v[152:155], v[196:199], v[40:43]
	v_mfma_f32_16x16x32_bf16 v[44:47], v[160:163], v[196:199], v[44:47]
	v_mfma_f32_16x16x32_bf16 v[64:67], v[152:155], v[204:207], v[64:67]
	v_mfma_f32_16x16x32_bf16 v[68:71], v[160:163], v[204:207], v[68:71]
	v_mfma_f32_16x16x32_bf16 v[88:91], v[152:155], v[212:215], v[88:91]
	v_mfma_f32_16x16x32_bf16 v[92:95], v[160:163], v[212:215], v[92:95]
	s_setprio 0
	s_setprio 1
	v_mfma_f32_16x16x32_bf16 v[28:31], v[164:167], v[184:187], v[28:31]
	v_mfma_f32_16x16x32_bf16 v[24:27], v[172:175], v[184:187], v[24:27]
	v_mfma_f32_16x16x32_bf16 v[48:51], v[164:167], v[192:195], v[48:51]
	v_mfma_f32_16x16x32_bf16 v[52:55], v[172:175], v[192:195], v[52:55]
	v_mfma_f32_16x16x32_bf16 v[72:75], v[164:167], v[200:203], v[72:75]
	v_mfma_f32_16x16x32_bf16 v[76:79], v[172:175], v[200:203], v[76:79]
	v_mfma_f32_16x16x32_bf16 v[96:99], v[164:167], v[208:211], v[96:99]
	v_mfma_f32_16x16x32_bf16 v[100:103], v[172:175], v[208:211], v[100:103]
	v_mfma_f32_16x16x32_bf16 v[28:31], v[168:171], v[188:191], v[28:31]
	v_mfma_f32_16x16x32_bf16 v[24:27], v[180:183], v[188:191], v[24:27]
	v_mfma_f32_16x16x32_bf16 v[48:51], v[168:171], v[196:199], v[48:51]
	v_mfma_f32_16x16x32_bf16 v[52:55], v[180:183], v[196:199], v[52:55]
	v_mfma_f32_16x16x32_bf16 v[72:75], v[168:171], v[204:207], v[72:75]
	v_mfma_f32_16x16x32_bf16 v[76:79], v[180:183], v[204:207], v[76:79]
	v_mfma_f32_16x16x32_bf16 v[96:99], v[168:171], v[212:215], v[96:99]
	v_mfma_f32_16x16x32_bf16 v[100:103], v[180:183], v[212:215], v[100:103]
	s_setprio 0
	s_barrier
	s_mov_b32 m0, s72
	v_lshl_add_u64 v[216:217], s[48:49], 0, v[130:131]
	s_add_u32 s34, s48, 0x80000
	global_load_lds_dwordx4 v[216:217], off
	v_lshl_add_u64 v[218:219], s[48:49], 0, v[134:135]
	s_mov_b32 m0, s73
	s_addc_u32 s35, s49, 0
	global_load_lds_dwordx4 v[218:219], off
	v_lshl_add_u64 v[138:139], s[34:35], 0, v[130:131]
	s_mov_b32 m0, s74
	v_lshl_add_u64 v[222:223], s[54:55], 0, v[128:129]
	global_load_lds_dwordx4 v[138:139], off
	v_lshl_add_u64 v[138:139], s[34:35], 0, v[134:135]
	s_mov_b32 m0, s76
	v_lshl_add_u64 v[224:225], s[54:55], 0, v[132:133]
	global_load_lds_dwordx4 v[138:139], off
	s_mov_b32 m0, s36
	s_nop 0
	global_load_lds_dwordx4 v[222:223], off
	s_mov_b32 m0, s37
	s_nop 0
	global_load_lds_dwordx4 v[224:225], off
	ds_read_b128 v[184:187], v146 offset:16384
	ds_read_b128 v[188:191], v146 offset:17408
	ds_read_b128 v[192:195], v146 offset:18432
	ds_read_b128 v[196:199], v146 offset:19456
	ds_read_b128 v[200:203], v146 offset:20480
	ds_read_b128 v[204:207], v146 offset:21504
	ds_read_b128 v[208:211], v146 offset:22528
	ds_read_b128 v[212:215], v146 offset:23552
	s_waitcnt vmcnt(8)
	s_waitcnt lgkmcnt(0)
	s_barrier
	s_setprio 1
	s_waitcnt lgkmcnt(0)
	v_mfma_f32_16x16x32_bf16 v[112:115], v[148:151], v[184:187], v[112:115]
	v_mfma_f32_16x16x32_bf16 v[116:119], v[156:159], v[184:187], v[116:119]
	v_mfma_f32_16x16x32_bf16 v[108:111], v[148:151], v[192:195], v[108:111]
	v_mfma_f32_16x16x32_bf16 v[104:107], v[156:159], v[192:195], v[104:107]
	v_mfma_f32_16x16x32_bf16 v[60:63], v[148:151], v[200:203], v[60:63]
	v_mfma_f32_16x16x32_bf16 v[56:59], v[156:159], v[200:203], v[56:59]
	v_mfma_f32_16x16x32_bf16 v[20:23], v[148:151], v[208:211], v[20:23]
	v_mfma_f32_16x16x32_bf16 v[16:19], v[156:159], v[208:211], v[16:19]
	v_mfma_f32_16x16x32_bf16 v[112:115], v[152:155], v[188:191], v[112:115]
	v_mfma_f32_16x16x32_bf16 v[116:119], v[160:163], v[188:191], v[116:119]
	v_mfma_f32_16x16x32_bf16 v[108:111], v[152:155], v[196:199], v[108:111]
	v_mfma_f32_16x16x32_bf16 v[104:107], v[160:163], v[196:199], v[104:107]
	v_mfma_f32_16x16x32_bf16 v[60:63], v[152:155], v[204:207], v[60:63]
	v_mfma_f32_16x16x32_bf16 v[56:59], v[160:163], v[204:207], v[56:59]
	v_mfma_f32_16x16x32_bf16 v[20:23], v[152:155], v[212:215], v[20:23]
	v_mfma_f32_16x16x32_bf16 v[16:19], v[160:163], v[212:215], v[16:19]
	s_setprio 0
	s_setprio 1
	v_mfma_f32_16x16x32_bf16 v[124:127], v[164:167], v[184:187], v[124:127]
	v_mfma_f32_16x16x32_bf16 v[120:123], v[172:175], v[184:187], v[120:123]
	v_mfma_f32_16x16x32_bf16 v[84:87], v[164:167], v[192:195], v[84:87]
	v_mfma_f32_16x16x32_bf16 v[80:83], v[172:175], v[192:195], v[80:83]
	v_mfma_f32_16x16x32_bf16 v[36:39], v[164:167], v[200:203], v[36:39]
	v_mfma_f32_16x16x32_bf16 v[32:35], v[172:175], v[200:203], v[32:35]
	v_mfma_f32_16x16x32_bf16 v[4:7], v[164:167], v[208:211], v[4:7]
	v_mfma_f32_16x16x32_bf16 v[0:3], v[172:175], v[208:211], v[0:3]
	v_mfma_f32_16x16x32_bf16 v[124:127], v[168:171], v[188:191], v[124:127]
	v_mfma_f32_16x16x32_bf16 v[120:123], v[180:183], v[188:191], v[120:123]
	v_mfma_f32_16x16x32_bf16 v[84:87], v[168:171], v[196:199], v[84:87]
	v_mfma_f32_16x16x32_bf16 v[80:83], v[180:183], v[196:199], v[80:83]
	v_mfma_f32_16x16x32_bf16 v[36:39], v[168:171], v[204:207], v[36:39]
	v_mfma_f32_16x16x32_bf16 v[32:35], v[180:183], v[204:207], v[32:35]
	v_mfma_f32_16x16x32_bf16 v[4:7], v[168:171], v[212:215], v[4:7]
	v_mfma_f32_16x16x32_bf16 v[0:3], v[180:183], v[212:215], v[0:3]
	s_setprio 0
	s_barrier
	s_add_i32 s82, 0, 0x1c000
	s_add_u32 s34, s54, 0x80000
	s_addc_u32 s35, s55, 0
	s_mov_b32 m0, s40
	v_lshl_add_u64 v[226:227], s[34:35], 0, v[128:129]
	global_load_lds_dwordx4 v[226:227], off
	v_lshl_add_u64 v[226:227], s[34:35], 0, v[132:133]
	s_mov_b32 m0, s41
	s_nop 0
	global_load_lds_dwordx4 v[226:227], off
	v_add_u32_e32 v138, s82, v140
	ds_read_b128 v[148:151], v147
	ds_read_b128 v[152:155], v147 offset:1024
	ds_read_b128 v[156:159], v147 offset:2048
	ds_read_b128 v[160:163], v147 offset:3072
	ds_read_b128 v[164:167], v138
	ds_read_b128 v[168:171], v138 offset:1024
	ds_read_b128 v[172:175], v138 offset:2048
	ds_read_b128 v[180:183], v138 offset:3072
	ds_read_b128 v[184:187], v146 offset:32768
	ds_read_b128 v[188:191], v146 offset:33792
	ds_read_b128 v[192:195], v146 offset:34816
	ds_read_b128 v[196:199], v146 offset:35840
	ds_read_b128 v[200:203], v146 offset:36864
	ds_read_b128 v[204:207], v146 offset:37888
	ds_read_b128 v[208:211], v146 offset:38912
	ds_read_b128 v[212:215], v146 offset:39936
	s_waitcnt vmcnt(8)
	s_waitcnt lgkmcnt(0)
	s_barrier
	s_setprio 1
	s_waitcnt lgkmcnt(0)
	v_mfma_f32_16x16x32_bf16 v[8:11], v[148:151], v[184:187], v[8:11]
	v_mfma_f32_16x16x32_bf16 v[12:15], v[156:159], v[184:187], v[12:15]
	v_mfma_f32_16x16x32_bf16 v[40:43], v[148:151], v[192:195], v[40:43]
	v_mfma_f32_16x16x32_bf16 v[44:47], v[156:159], v[192:195], v[44:47]
	v_mfma_f32_16x16x32_bf16 v[64:67], v[148:151], v[200:203], v[64:67]
	v_mfma_f32_16x16x32_bf16 v[68:71], v[156:159], v[200:203], v[68:71]
	v_mfma_f32_16x16x32_bf16 v[88:91], v[148:151], v[208:211], v[88:91]
	v_mfma_f32_16x16x32_bf16 v[92:95], v[156:159], v[208:211], v[92:95]
	v_mfma_f32_16x16x32_bf16 v[8:11], v[152:155], v[188:191], v[8:11]
	v_mfma_f32_16x16x32_bf16 v[12:15], v[160:163], v[188:191], v[12:15]
	v_mfma_f32_16x16x32_bf16 v[40:43], v[152:155], v[196:199], v[40:43]
	v_mfma_f32_16x16x32_bf16 v[44:47], v[160:163], v[196:199], v[44:47]
	v_mfma_f32_16x16x32_bf16 v[64:67], v[152:155], v[204:207], v[64:67]
	v_mfma_f32_16x16x32_bf16 v[68:71], v[160:163], v[204:207], v[68:71]
	v_mfma_f32_16x16x32_bf16 v[88:91], v[152:155], v[212:215], v[88:91]
	v_mfma_f32_16x16x32_bf16 v[92:95], v[160:163], v[212:215], v[92:95]
	s_setprio 0
	s_setprio 1
	v_mfma_f32_16x16x32_bf16 v[28:31], v[164:167], v[184:187], v[28:31]
	v_mfma_f32_16x16x32_bf16 v[24:27], v[172:175], v[184:187], v[24:27]
	v_mfma_f32_16x16x32_bf16 v[48:51], v[164:167], v[192:195], v[48:51]
	v_mfma_f32_16x16x32_bf16 v[52:55], v[172:175], v[192:195], v[52:55]
	v_mfma_f32_16x16x32_bf16 v[72:75], v[164:167], v[200:203], v[72:75]
	v_mfma_f32_16x16x32_bf16 v[76:79], v[172:175], v[200:203], v[76:79]
	v_mfma_f32_16x16x32_bf16 v[96:99], v[164:167], v[208:211], v[96:99]
	v_mfma_f32_16x16x32_bf16 v[100:103], v[172:175], v[208:211], v[100:103]
	v_mfma_f32_16x16x32_bf16 v[28:31], v[168:171], v[188:191], v[28:31]
	v_mfma_f32_16x16x32_bf16 v[24:27], v[180:183], v[188:191], v[24:27]
	v_mfma_f32_16x16x32_bf16 v[48:51], v[168:171], v[196:199], v[48:51]
	v_mfma_f32_16x16x32_bf16 v[52:55], v[180:183], v[196:199], v[52:55]
	v_mfma_f32_16x16x32_bf16 v[72:75], v[168:171], v[204:207], v[72:75]
	v_mfma_f32_16x16x32_bf16 v[76:79], v[180:183], v[204:207], v[76:79]
	v_mfma_f32_16x16x32_bf16 v[96:99], v[168:171], v[212:215], v[96:99]
	v_mfma_f32_16x16x32_bf16 v[100:103], v[180:183], v[212:215], v[100:103]
	s_setprio 0
	s_barrier
;         unsigned lo_ = (unsigned)((wr * 64 + fr) * PLD + wc * 32 + 8 * fq) * 2u; asm volatile("" : "+v"(lo_));
;         const char* pb = (const char*)proj + (((size_t)u.pm * 256 + u.ra) * PLD + u.pn * 256 + u.cb) * 2;
; #pragma unroll
;         for (int ai = 0; ai < NAI; ++ai)
; #pragma unroll
;             for (int m = 0; m < 4; ++m) {
; #pragma unroll
;                 for (int bj = 0; bj < NBJ; ++bj) {
;                     const unsigned off = lo_ + (unsigned)(((ai * 128 + m * 16) * PLD + bj * 128) * 2);
;                     const u32x4 rv = *(const u32x4*)(pb + off + PC_GA * 2);
	s_add_i32 s80, s77, s14
	s_add_i32 s81, s80, 0x2000
	v_lshl_add_u64 v[216:217], v[216:217], 0, s[22:23]
	s_mov_b32 m0, s80
	s_add_u32 s34, s48, 0x80080
	global_load_lds_dwordx4 v[216:217], off
	v_lshl_add_u64 v[216:217], v[218:219], 0, s[22:23]
	s_mov_b32 m0, s81
	s_addc_u32 s35, s49, 0
	s_add_i32 s82, s82, s14
	global_load_lds_dwordx4 v[216:217], off
	v_lshl_add_u64 v[216:217], s[34:35], 0, v[130:131]
	s_mov_b32 m0, s82
	s_add_i32 s83, s82, 0x2000
	global_load_lds_dwordx4 v[216:217], off
	v_lshl_add_u64 v[216:217], s[34:35], 0, v[134:135]
	s_mov_b32 m0, s83
	s_nop 0
	global_load_lds_dwordx4 v[216:217], off
	v_lshl_add_u64 v[216:217], v[222:223], 0, s[22:23]
	s_mov_b32 m0, s43
	s_nop 0
	global_load_lds_dwordx4 v[216:217], off
	v_lshl_add_u64 v[216:217], v[224:225], 0, s[22:23]
	s_mov_b32 m0, s64
	s_nop 0
	global_load_lds_dwordx4 v[216:217], off
	ds_read_b128 v[184:187], v146 offset:49152
	ds_read_b128 v[188:191], v146 offset:50176
	ds_read_b128 v[192:195], v146 offset:51200
	ds_read_b128 v[196:199], v146 offset:52224
	ds_read_b128 v[200:203], v146 offset:53248
	ds_read_b128 v[204:207], v146 offset:54272
	ds_read_b128 v[208:211], v146 offset:55296
	ds_read_b128 v[212:215], v146 offset:56320
	s_waitcnt vmcnt(8)
	s_waitcnt lgkmcnt(0)
	s_barrier
	s_setprio 1
	s_waitcnt lgkmcnt(0)
	v_mfma_f32_16x16x32_bf16 v[112:115], v[148:151], v[184:187], v[112:115]
	v_mfma_f32_16x16x32_bf16 v[116:119], v[156:159], v[184:187], v[116:119]
	v_mfma_f32_16x16x32_bf16 v[108:111], v[148:151], v[192:195], v[108:111]
	v_mfma_f32_16x16x32_bf16 v[104:107], v[156:159], v[192:195], v[104:107]
	v_mfma_f32_16x16x32_bf16 v[60:63], v[148:151], v[200:203], v[60:63]
	v_mfma_f32_16x16x32_bf16 v[56:59], v[156:159], v[200:203], v[56:59]
	v_mfma_f32_16x16x32_bf16 v[20:23], v[148:151], v[208:211], v[20:23]
	v_mfma_f32_16x16x32_bf16 v[16:19], v[156:159], v[208:211], v[16:19]
	v_mfma_f32_16x16x32_bf16 v[112:115], v[152:155], v[188:191], v[112:115]
	v_mfma_f32_16x16x32_bf16 v[116:119], v[160:163], v[188:191], v[116:119]
	v_mfma_f32_16x16x32_bf16 v[108:111], v[152:155], v[196:199], v[108:111]
	v_mfma_f32_16x16x32_bf16 v[104:107], v[160:163], v[196:199], v[104:107]
	v_mfma_f32_16x16x32_bf16 v[60:63], v[152:155], v[204:207], v[60:63]
	v_mfma_f32_16x16x32_bf16 v[56:59], v[160:163], v[204:207], v[56:59]
	v_mfma_f32_16x16x32_bf16 v[20:23], v[152:155], v[212:215], v[20:23]
	v_mfma_f32_16x16x32_bf16 v[16:19], v[160:163], v[212:215], v[16:19]
	s_setprio 0
	s_setprio 1
	v_mfma_f32_16x16x32_bf16 v[124:127], v[164:167], v[184:187], v[124:127]
	v_mfma_f32_16x16x32_bf16 v[120:123], v[172:175], v[184:187], v[120:123]
	v_mfma_f32_16x16x32_bf16 v[84:87], v[164:167], v[192:195], v[84:87]
	v_mfma_f32_16x16x32_bf16 v[80:83], v[172:175], v[192:195], v[80:83]
	v_mfma_f32_16x16x32_bf16 v[36:39], v[164:167], v[200:203], v[36:39]
	v_mfma_f32_16x16x32_bf16 v[32:35], v[172:175], v[200:203], v[32:35]
	v_mfma_f32_16x16x32_bf16 v[4:7], v[164:167], v[208:211], v[4:7]
	v_mfma_f32_16x16x32_bf16 v[0:3], v[172:175], v[208:211], v[0:3]
	v_mfma_f32_16x16x32_bf16 v[124:127], v[168:171], v[188:191], v[124:127]
	v_mfma_f32_16x16x32_bf16 v[120:123], v[180:183], v[188:191], v[120:123]
	v_mfma_f32_16x16x32_bf16 v[84:87], v[168:171], v[196:199], v[84:87]
	v_mfma_f32_16x16x32_bf16 v[80:83], v[180:183], v[196:199], v[80:83]
	v_mfma_f32_16x16x32_bf16 v[36:39], v[168:171], v[204:207], v[36:39]
	v_mfma_f32_16x16x32_bf16 v[32:35], v[180:183], v[204:207], v[32:35]
	v_mfma_f32_16x16x32_bf16 v[4:7], v[168:171], v[212:215], v[4:7]
	v_mfma_f32_16x16x32_bf16 v[0:3], v[180:183], v[212:215], v[0:3]
	s_setprio 0
	s_barrier
	s_add_i32 s57, s57, 2
	s_add_u32 s0, s0, 0x100
	s_addc_u32 s1, s1, 0
	s_add_u32 s9, s9, 0x100
	s_addc_u32 s56, s56, 0
	s_cmp_gt_u32 s57, 13
	s_cbranch_scc0 .LBB0_701
	s_lshl_b32 s54, s10, 8
	s_mul_i32 s0, s8, 0x240000
	s_ashr_i32 s55, s54, 31
	s_mul_hi_i32 s1, s8, 0x240000
	s_add_u32 s0, s0, s54
	s_addc_u32 s1, s1, s55
	s_lshl_b64 s[0:1], s[0:1], 1
	s_add_u32 s48, s16, s0
	s_addc_u32 s49, s17, s1
	s_add_i32 s78, s78, 1
	s_mul_i32 s0, s78, s65
	s_mul_hi_u32 s1, s78, s3
	s_add_i32 s1, s1, s0
	s_mul_i32 s0, s78, s3
	s_add_u32 s56, s0, s2
	s_addc_u32 s57, s1, s15
	s_mov_b32 s9, s8
	v_mov_b32_e32 v136, v141
	v_lshl_add_u64 v[148:149], s[48:49], 0, v[136:137]
	v_add_co_u32_e32 v148, vcc, s42, v148
	s_mov_b32 s85, 0
	s_nop 0
	v_addc_co_u32_e32 v149, vcc, 0, v149, vcc
	global_load_dwordx4 v[180:183], v[148:149], off offset:2048
	s_mov_b32 s84, 0x100
	v_lshl_add_u64 v[150:151], v[148:149], 0, s[84:85]
	global_load_dwordx4 v[184:187], v[150:151], off offset:2048
	s_mov_b32 s84, 0x48000
	v_lshl_add_u64 v[152:153], v[148:149], 0, s[84:85]
	global_load_dwordx4 v[188:191], v[152:153], off offset:2048
	s_mov_b32 s84, 0x48100
	v_lshl_add_u64 v[150:151], v[148:149], 0, s[84:85]
	global_load_dwordx4 v[192:195], v[150:151], off offset:2048
	s_mov_b32 s84, 0x90000
	v_lshl_add_u64 v[152:153], v[148:149], 0, s[84:85]
	global_load_dwordx4 v[196:199], v[152:153], off offset:2048
	s_mov_b32 s84, 0x90100
	v_lshl_add_u64 v[150:151], v[148:149], 0, s[84:85]
	global_load_dwordx4 v[200:203], v[150:151], off offset:2048
	s_mov_b32 s84, 0xd8000
	v_lshl_add_u64 v[152:153], v[148:149], 0, s[84:85]
	global_load_dwordx4 v[204:207], v[152:153], off offset:2048
	s_mov_b32 s84, 0xd8100
	v_lshl_add_u64 v[150:151], v[148:149], 0, s[84:85]
	global_load_dwordx4 v[208:211], v[150:151], off offset:2048
	s_mov_b32 s84, 0x240000
	v_lshl_add_u64 v[152:153], v[148:149], 0, s[84:85]
	global_load_dwordx4 v[212:215], v[152:153], off offset:2048
	s_mov_b32 s84, 0x240100
	v_lshl_add_u64 v[150:151], v[148:149], 0, s[84:85]
	global_load_dwordx4 v[216:219], v[150:151], off offset:2048
	s_mov_b32 s84, 0x288000
	v_lshl_add_u64 v[152:153], v[148:149], 0, s[84:85]
	global_load_dwordx4 v[224:227], v[152:153], off offset:2048
	s_mov_b32 s84, 0x288100
	v_lshl_add_u64 v[150:151], v[148:149], 0, s[84:85]
	global_load_dwordx4 v[228:231], v[150:151], off offset:2048
	s_mov_b32 s84, 0x2d0000
	v_lshl_add_u64 v[152:153], v[148:149], 0, s[84:85]
	global_load_dwordx4 v[232:235], v[152:153], off offset:2048
	s_mov_b32 s84, 0x2d0100
	v_lshl_add_u64 v[150:151], v[148:149], 0, s[84:85]
	global_load_dwordx4 v[236:239], v[150:151], off offset:2048
	s_mov_b32 s84, 0x318000
	v_lshl_add_u64 v[152:153], v[148:149], 0, s[84:85]
	global_load_dwordx4 v[240:243], v[152:153], off offset:2048
	s_mov_b32 s84, 0x318100
	v_lshl_add_u64 v[150:151], v[148:149], 0, s[84:85]
	global_load_dwordx4 v[244:247], v[150:151], off offset:2048
	s_waitcnt vmcnt(15)
;     ...
;             for (int m = 0; m < 4; ++m) {
; #pragma unroll
;                 for (int bj = 0; bj < NBJ; ++bj) {
;                     const unsigned off = lo_ + (unsigned)(((ai * 128 + m * 16) * PLD + bj * 128) * 2);
;                     const u32x4 rv = *(const u32x4*)(pb + off + PC_GA * 2);
;                     acc[ai][bj][m][0][0] *= bflo(rv[0]); acc[ai][bj][m][0][1] *= bfhi(rv[0]); acc[ai][bj][m][0][2] *= bflo(rv[1]); acc[ai][bj][m][0][3] *= bfhi(rv[1]);
;                     acc[ai][bj][m][1][0] *= bflo(rv[2]); acc[ai][bj][m][1][1] *= bfhi(rv[2]); acc[ai][bj][m][1][2] *= bflo(rv[3]); acc[ai][bj][m][1][3] *= bfhi(rv[3]);
;                     asm volatile("" : "+v"(acc[ai][bj][m][0]), "+v"(acc[ai][bj][m][1]) :: "memory");
	v_lshlrev_b32_e32 v148, 16, v180
	v_and_b32_e32 v149, 0xffff0000, v180
	v_pk_mul_f32 v[8:9], v[8:9], v[148:149]
	v_lshlrev_b32_e32 v150, 16, v181
	v_and_b32_e32 v151, 0xffff0000, v181
	v_pk_mul_f32 v[10:11], v[10:11], v[150:151]
	v_lshlrev_b32_e32 v148, 16, v182
	v_and_b32_e32 v149, 0xffff0000, v182
	v_pk_mul_f32 v[12:13], v[12:13], v[148:149]
	v_lshlrev_b32_e32 v150, 16, v183
	v_and_b32_e32 v151, 0xffff0000, v183
	v_pk_mul_f32 v[14:15], v[14:15], v[150:151]
	s_waitcnt vmcnt(14)
	v_lshlrev_b32_e32 v148, 16, v184
	v_and_b32_e32 v149, 0xffff0000, v184
	v_pk_mul_f32 v[28:29], v[28:29], v[148:149]
	v_lshlrev_b32_e32 v150, 16, v185
	v_and_b32_e32 v151, 0xffff0000, v185
	v_pk_mul_f32 v[30:31], v[30:31], v[150:151]
	v_lshlrev_b32_e32 v148, 16, v186
	v_and_b32_e32 v149, 0xffff0000, v186
	v_pk_mul_f32 v[24:25], v[24:25], v[148:149]
	v_lshlrev_b32_e32 v150, 16, v187
	v_and_b32_e32 v151, 0xffff0000, v187
	v_pk_mul_f32 v[26:27], v[26:27], v[150:151]
	s_waitcnt vmcnt(13)
	v_lshlrev_b32_e32 v148, 16, v188
	v_and_b32_e32 v149, 0xffff0000, v188
	v_pk_mul_f32 v[40:41], v[40:41], v[148:149]
	v_lshlrev_b32_e32 v150, 16, v189
	v_and_b32_e32 v151, 0xffff0000, v189
	v_pk_mul_f32 v[42:43], v[42:43], v[150:151]
	v_lshlrev_b32_e32 v148, 16, v190
	v_and_b32_e32 v149, 0xffff0000, v190
	v_pk_mul_f32 v[44:45], v[44:45], v[148:149]
	v_lshlrev_b32_e32 v150, 16, v191
	v_and_b32_e32 v151, 0xffff0000, v191
	v_pk_mul_f32 v[46:47], v[46:47], v[150:151]
	s_waitcnt vmcnt(12)
	v_lshlrev_b32_e32 v148, 16, v192
	v_and_b32_e32 v149, 0xffff0000, v192
	v_pk_mul_f32 v[48:49], v[48:49], v[148:149]
	v_lshlrev_b32_e32 v150, 16, v193
	v_and_b32_e32 v151, 0xffff0000, v193
	v_pk_mul_f32 v[50:51], v[50:51], v[150:151]
	v_lshlrev_b32_e32 v148, 16, v194
	v_and_b32_e32 v149, 0xffff0000, v194
	v_pk_mul_f32 v[52:53], v[52:53], v[148:149]
	v_lshlrev_b32_e32 v150, 16, v195
	v_and_b32_e32 v151, 0xffff0000, v195
	v_pk_mul_f32 v[54:55], v[54:55], v[150:151]
	s_waitcnt vmcnt(11)
	v_lshlrev_b32_e32 v148, 16, v196
	v_and_b32_e32 v149, 0xffff0000, v196
	v_pk_mul_f32 v[64:65], v[64:65], v[148:149]
	v_lshlrev_b32_e32 v150, 16, v197
	v_and_b32_e32 v151, 0xffff0000, v197
	v_pk_mul_f32 v[66:67], v[66:67], v[150:151]
	v_lshlrev_b32_e32 v148, 16, v198
	v_and_b32_e32 v149, 0xffff0000, v198
	v_pk_mul_f32 v[68:69], v[68:69], v[148:149]
	v_lshlrev_b32_e32 v150, 16, v199
	v_and_b32_e32 v151, 0xffff0000, v199
	v_pk_mul_f32 v[70:71], v[70:71], v[150:151]
	s_waitcnt vmcnt(10)
	v_lshlrev_b32_e32 v148, 16, v200
	v_and_b32_e32 v149, 0xffff0000, v200
	v_pk_mul_f32 v[72:73], v[72:73], v[148:149]
	v_lshlrev_b32_e32 v150, 16, v201
	v_and_b32_e32 v151, 0xffff0000, v201
	v_pk_mul_f32 v[74:75], v[74:75], v[150:151]
	v_lshlrev_b32_e32 v148, 16, v202
	v_and_b32_e32 v149, 0xffff0000, v202
	v_pk_mul_f32 v[76:77], v[76:77], v[148:149]
	v_lshlrev_b32_e32 v150, 16, v203
	v_and_b32_e32 v151, 0xffff0000, v203
	v_pk_mul_f32 v[78:79], v[78:79], v[150:151]
	s_waitcnt vmcnt(9)
	v_lshlrev_b32_e32 v148, 16, v204
	v_and_b32_e32 v149, 0xffff0000, v204
	v_pk_mul_f32 v[88:89], v[88:89], v[148:149]
	v_lshlrev_b32_e32 v150, 16, v205
	v_and_b32_e32 v151, 0xffff0000, v205
	v_pk_mul_f32 v[90:91], v[90:91], v[150:151]
	v_lshlrev_b32_e32 v148, 16, v206
	v_and_b32_e32 v149, 0xffff0000, v206
	v_pk_mul_f32 v[92:93], v[92:93], v[148:149]
	v_lshlrev_b32_e32 v150, 16, v207
	v_and_b32_e32 v151, 0xffff0000, v207
	v_pk_mul_f32 v[94:95], v[94:95], v[150:151]
	s_waitcnt vmcnt(8)
	v_lshlrev_b32_e32 v148, 16, v208
	v_and_b32_e32 v149, 0xffff0000, v208
	v_pk_mul_f32 v[96:97], v[96:97], v[148:149]
	v_lshlrev_b32_e32 v150, 16, v209
	v_and_b32_e32 v151, 0xffff0000, v209
	v_pk_mul_f32 v[98:99], v[98:99], v[150:151]
	v_lshlrev_b32_e32 v148, 16, v210
	v_and_b32_e32 v149, 0xffff0000, v210
	v_pk_mul_f32 v[100:101], v[100:101], v[148:149]
	v_lshlrev_b32_e32 v150, 16, v211
	v_and_b32_e32 v151, 0xffff0000, v211
	v_pk_mul_f32 v[102:103], v[102:103], v[150:151]
	s_waitcnt vmcnt(7)
	v_lshlrev_b32_e32 v148, 16, v212
	v_and_b32_e32 v149, 0xffff0000, v212
	v_pk_mul_f32 v[112:113], v[112:113], v[148:149]
	v_lshlrev_b32_e32 v150, 16, v213
	v_and_b32_e32 v151, 0xffff0000, v213
	v_pk_mul_f32 v[114:115], v[114:115], v[150:151]
	v_lshlrev_b32_e32 v148, 16, v214
	v_and_b32_e32 v149, 0xffff0000, v214
	v_pk_mul_f32 v[116:117], v[116:117], v[148:149]
	v_lshlrev_b32_e32 v150, 16, v215
	v_and_b32_e32 v151, 0xffff0000, v215
	v_pk_mul_f32 v[118:119], v[118:119], v[150:151]
	s_waitcnt vmcnt(6)
;     __device__ bool next(int i, Unit& u) const {
;         const long L = (long)i * G + c; if (L >= lim) return false;
;         unit_of((int)L, u); return true;
;     ...
;                     acc[ai][bj][m][0][0] *= bflo(rv[0]); acc[ai][bj][m][0][1] *= bfhi(rv[0]); acc[ai][bj][m][0][2] *= bflo(rv[1]); acc[ai][bj][m][0][3] *= bfhi(rv[1]);
;                     acc[ai][bj][m][1][0] *= bflo(rv[2]); acc[ai][bj][m][1][1] *= bfhi(rv[2]); acc[ai][bj][m][1][2] *= bflo(rv[3]); acc[ai][bj][m][1][3] *= bfhi(rv[3]);
;                     asm volatile("" : "+v"(acc[ai][bj][m][0]), "+v"(acc[ai][bj][m][1]) :: "memory");
	v_lshlrev_b32_e32 v148, 16, v216
	v_and_b32_e32 v149, 0xffff0000, v216
	v_pk_mul_f32 v[124:125], v[124:125], v[148:149]
	v_lshlrev_b32_e32 v150, 16, v217
	v_and_b32_e32 v151, 0xffff0000, v217
	v_pk_mul_f32 v[126:127], v[126:127], v[150:151]
	v_lshlrev_b32_e32 v148, 16, v218
	v_and_b32_e32 v149, 0xffff0000, v218
	v_pk_mul_f32 v[120:121], v[120:121], v[148:149]
	v_lshlrev_b32_e32 v150, 16, v219
	v_and_b32_e32 v151, 0xffff0000, v219
	v_pk_mul_f32 v[122:123], v[122:123], v[150:151]
	s_waitcnt vmcnt(5)
	v_lshlrev_b32_e32 v148, 16, v224
	v_and_b32_e32 v149, 0xffff0000, v224
	v_pk_mul_f32 v[108:109], v[108:109], v[148:149]
	v_lshlrev_b32_e32 v150, 16, v225
	v_and_b32_e32 v151, 0xffff0000, v225
	v_pk_mul_f32 v[110:111], v[110:111], v[150:151]
	v_lshlrev_b32_e32 v148, 16, v226
	v_and_b32_e32 v149, 0xffff0000, v226
	v_pk_mul_f32 v[104:105], v[104:105], v[148:149]
	v_lshlrev_b32_e32 v150, 16, v227
	v_and_b32_e32 v151, 0xffff0000, v227
	v_pk_mul_f32 v[106:107], v[106:107], v[150:151]
	s_waitcnt vmcnt(4)
	v_lshlrev_b32_e32 v148, 16, v228
	v_and_b32_e32 v149, 0xffff0000, v228
	v_pk_mul_f32 v[84:85], v[84:85], v[148:149]
	v_lshlrev_b32_e32 v150, 16, v229
	v_and_b32_e32 v151, 0xffff0000, v229
	v_pk_mul_f32 v[86:87], v[86:87], v[150:151]
	v_lshlrev_b32_e32 v148, 16, v230
	v_and_b32_e32 v149, 0xffff0000, v230
	v_pk_mul_f32 v[80:81], v[80:81], v[148:149]
	v_lshlrev_b32_e32 v150, 16, v231
	v_and_b32_e32 v151, 0xffff0000, v231
	v_pk_mul_f32 v[82:83], v[82:83], v[150:151]
	s_waitcnt vmcnt(3)
	v_lshlrev_b32_e32 v148, 16, v232
	v_and_b32_e32 v149, 0xffff0000, v232
	v_pk_mul_f32 v[60:61], v[60:61], v[148:149]
	v_lshlrev_b32_e32 v150, 16, v233
	v_and_b32_e32 v151, 0xffff0000, v233
	v_pk_mul_f32 v[62:63], v[62:63], v[150:151]
	v_lshlrev_b32_e32 v148, 16, v234
	v_and_b32_e32 v149, 0xffff0000, v234
	v_pk_mul_f32 v[56:57], v[56:57], v[148:149]
	v_lshlrev_b32_e32 v150, 16, v235
	v_and_b32_e32 v151, 0xffff0000, v235
	v_pk_mul_f32 v[58:59], v[58:59], v[150:151]
	s_waitcnt vmcnt(2)
	v_lshlrev_b32_e32 v148, 16, v236
	v_and_b32_e32 v149, 0xffff0000, v236
	v_pk_mul_f32 v[36:37], v[36:37], v[148:149]
	v_lshlrev_b32_e32 v150, 16, v237
	v_and_b32_e32 v151, 0xffff0000, v237
	v_pk_mul_f32 v[38:39], v[38:39], v[150:151]
	v_lshlrev_b32_e32 v148, 16, v238
	v_and_b32_e32 v149, 0xffff0000, v238
	v_pk_mul_f32 v[32:33], v[32:33], v[148:149]
	v_lshlrev_b32_e32 v150, 16, v239
	v_and_b32_e32 v151, 0xffff0000, v239
	v_pk_mul_f32 v[34:35], v[34:35], v[150:151]
	s_waitcnt vmcnt(1)
	v_lshlrev_b32_e32 v148, 16, v240
	v_and_b32_e32 v149, 0xffff0000, v240
	v_pk_mul_f32 v[20:21], v[20:21], v[148:149]
	v_lshlrev_b32_e32 v150, 16, v241
	v_and_b32_e32 v151, 0xffff0000, v241
	v_pk_mul_f32 v[22:23], v[22:23], v[150:151]
	v_lshlrev_b32_e32 v148, 16, v242
	v_and_b32_e32 v149, 0xffff0000, v242
	v_pk_mul_f32 v[16:17], v[16:17], v[148:149]
	v_lshlrev_b32_e32 v150, 16, v243
	v_and_b32_e32 v151, 0xffff0000, v243
	v_pk_mul_f32 v[18:19], v[18:19], v[150:151]
	s_waitcnt vmcnt(0)
	v_lshlrev_b32_e32 v148, 16, v244
	v_and_b32_e32 v149, 0xffff0000, v244
	v_pk_mul_f32 v[4:5], v[4:5], v[148:149]
	v_lshlrev_b32_e32 v150, 16, v245
	v_and_b32_e32 v151, 0xffff0000, v245
	v_pk_mul_f32 v[6:7], v[6:7], v[150:151]
	v_lshlrev_b32_e32 v148, 16, v246
	v_and_b32_e32 v149, 0xffff0000, v246
	v_pk_mul_f32 v[0:1], v[0:1], v[148:149]
	v_lshlrev_b32_e32 v150, 16, v247
	v_and_b32_e32 v151, 0xffff0000, v247
	v_pk_mul_f32 v[2:3], v[2:3], v[150:151]
	v_mov_b64_e32 v[148:149], s[6:7]
	v_cmp_ge_i64_e32 vcc, s[56:57], v[148:149]
	v_cmp_lt_i64_e64 s[0:1], s[56:57], v[148:149]
	s_cbranch_vccnz .LBB0_704
	s_ashr_i32 s9, s56, 31
	s_lshr_b32 s9, s9, 29
	s_add_i32 s9, s56, s9
	s_ashr_i32 s10, s9, 3
	s_and_b32 s9, s9, -8
	s_sub_i32 s9, s56, s9
	s_cmp_lt_i32 s9, 0
	s_cselect_b32 s34, s33, 0x44
	s_mul_i32 s9, s9, s34
	s_add_i32 s9, s9, s10
	s_ashr_i32 s10, s9, 31
	s_lshr_b32 s10, s10, 26
	s_add_i32 s10, s9, s10
	s_ashr_i32 s34, s10, 6
	s_lshl_b32 s34, s34, 3
	s_sub_i32 s35, 0x44, s34
	s_min_i32 s35, s35, 8
	s_abs_i32 s56, s35
	v_cvt_f32_u32_e32 v136, s56
	s_sub_i32 s58, 0, s56
	s_andn2_b32 s10, s10, 63
	s_sub_i32 s9, s9, s10
	v_rcp_iflag_f32_e32 v136, v136
	s_abs_i32 s10, s9
	s_xor_b32 s57, s9, s35
	s_ashr_i32 s57, s57, 31
	v_mul_f32_e32 v136, 0x4f7ffffe, v136
	v_cvt_u32_f32_e32 v136, v136
	s_nop 0
	v_readfirstlane_b32 s59, v136
	s_mul_i32 s58, s58, s59
	s_mul_hi_u32 s58, s59, s58
	s_add_i32 s59, s59, s58
	s_mul_hi_u32 s58, s10, s59
	s_mul_i32 s59, s58, s56
	s_sub_i32 s10, s10, s59
	s_add_i32 s60, s58, 1
	s_sub_i32 s59, s10, s56
	s_cmp_ge_u32 s10, s56
	s_cselect_b32 s58, s60, s58
	s_cselect_b32 s10, s59, s10
	s_add_i32 s59, s58, 1
	s_cmp_ge_u32 s10, s56
	s_cselect_b32 s10, s59, s58
	s_xor_b32 s10, s10, s57
	s_sub_i32 s10, s10, s57
	s_mul_i32 s35, s10, s35
	s_sub_i32 s9, s9, s35
	s_add_i32 s9, s34, s9

.LBB0_705:
	s_mov_b32 m0, s66
	v_lshl_add_u64 v[216:217], s[50:51], 0, v[128:129]
	global_load_lds_dwordx4 v[216:217], off
	v_lshl_add_u64 v[216:217], s[50:51], 0, v[132:133]
	s_mov_b32 m0, s67
	s_nop 0
	global_load_lds_dwordx4 v[216:217], off
	ds_read_b128 v[148:151], v144
	ds_read_b128 v[152:155], v144 offset:1024
	ds_read_b128 v[156:159], v144 offset:2048
	ds_read_b128 v[160:163], v144 offset:3072
	ds_read_b128 v[164:167], v145
	ds_read_b128 v[168:171], v145 offset:1024
	ds_read_b128 v[172:175], v145 offset:2048
	ds_read_b128 v[180:183], v145 offset:3072
	s_add_u32 s52, s50, 0xfff80080
	s_addc_u32 s53, s51, -1
	s_cmp_eq_u32 s85, 12
	s_cselect_b32 s63, s9, s53
	s_cselect_b32 s62, s34, s52
	s_cselect_b32 s53, s11, s84
	s_cselect_b32 s52, s35, s79
	ds_read_b128 v[184:187], v146
	ds_read_b128 v[188:191], v146 offset:1024
	ds_read_b128 v[192:195], v146 offset:2048
	ds_read_b128 v[196:199], v146 offset:3072
	ds_read_b128 v[200:203], v146 offset:4096
	ds_read_b128 v[204:207], v146 offset:5120
	ds_read_b128 v[208:211], v146 offset:6144
	ds_read_b128 v[212:215], v146 offset:7168
	s_waitcnt vmcnt(8)
	s_waitcnt lgkmcnt(0)
	s_barrier
	s_setprio 1
	s_waitcnt lgkmcnt(0)
	v_mfma_f32_16x16x32_bf16 v[8:11], v[148:151], v[184:187], v[8:11]
	v_mfma_f32_16x16x32_bf16 v[12:15], v[156:159], v[184:187], v[12:15]
	v_mfma_f32_16x16x32_bf16 v[40:43], v[148:151], v[192:195], v[40:43]
	v_mfma_f32_16x16x32_bf16 v[44:47], v[156:159], v[192:195], v[44:47]
	v_mfma_f32_16x16x32_bf16 v[64:67], v[148:151], v[200:203], v[64:67]
	v_mfma_f32_16x16x32_bf16 v[68:71], v[156:159], v[200:203], v[68:71]
	v_mfma_f32_16x16x32_bf16 v[88:91], v[148:151], v[208:211], v[88:91]
	v_mfma_f32_16x16x32_bf16 v[92:95], v[156:159], v[208:211], v[92:95]
	v_mfma_f32_16x16x32_bf16 v[8:11], v[152:155], v[188:191], v[8:11]
	v_mfma_f32_16x16x32_bf16 v[12:15], v[160:163], v[188:191], v[12:15]
	v_mfma_f32_16x16x32_bf16 v[40:43], v[152:155], v[196:199], v[40:43]
	v_mfma_f32_16x16x32_bf16 v[44:47], v[160:163], v[196:199], v[44:47]
	v_mfma_f32_16x16x32_bf16 v[64:67], v[152:155], v[204:207], v[64:67]
	v_mfma_f32_16x16x32_bf16 v[68:71], v[160:163], v[204:207], v[68:71]
	v_mfma_f32_16x16x32_bf16 v[88:91], v[152:155], v[212:215], v[88:91]
	v_mfma_f32_16x16x32_bf16 v[92:95], v[160:163], v[212:215], v[92:95]
	s_setprio 0
	s_setprio 1
	v_mfma_f32_16x16x32_bf16 v[28:31], v[164:167], v[184:187], v[28:31]
	v_mfma_f32_16x16x32_bf16 v[24:27], v[172:175], v[184:187], v[24:27]
	v_mfma_f32_16x16x32_bf16 v[48:51], v[164:167], v[192:195], v[48:51]
	v_mfma_f32_16x16x32_bf16 v[52:55], v[172:175], v[192:195], v[52:55]
	v_mfma_f32_16x16x32_bf16 v[72:75], v[164:167], v[200:203], v[72:75]
	v_mfma_f32_16x16x32_bf16 v[76:79], v[172:175], v[200:203], v[76:79]
	v_mfma_f32_16x16x32_bf16 v[96:99], v[164:167], v[208:211], v[96:99]
	v_mfma_f32_16x16x32_bf16 v[100:103], v[172:175], v[208:211], v[100:103]
	v_mfma_f32_16x16x32_bf16 v[28:31], v[168:171], v[188:191], v[28:31]
	v_mfma_f32_16x16x32_bf16 v[24:27], v[180:183], v[188:191], v[24:27]
	v_mfma_f32_16x16x32_bf16 v[48:51], v[168:171], v[196:199], v[48:51]
	v_mfma_f32_16x16x32_bf16 v[52:55], v[180:183], v[196:199], v[52:55]
	v_mfma_f32_16x16x32_bf16 v[72:75], v[168:171], v[204:207], v[72:75]
	v_mfma_f32_16x16x32_bf16 v[76:79], v[180:183], v[204:207], v[76:79]
	v_mfma_f32_16x16x32_bf16 v[96:99], v[168:171], v[212:215], v[96:99]
	v_mfma_f32_16x16x32_bf16 v[100:103], v[180:183], v[212:215], v[100:103]
	s_setprio 0
	s_barrier
	s_mov_b32 m0, s72
	v_lshl_add_u64 v[216:217], s[52:53], 0, v[130:131]
	s_add_u32 s86, s52, 0x80000
	global_load_lds_dwordx4 v[216:217], off
	v_lshl_add_u64 v[218:219], s[52:53], 0, v[134:135]
	s_mov_b32 m0, s73
	s_addc_u32 s87, s53, 0
	global_load_lds_dwordx4 v[218:219], off
	v_lshl_add_u64 v[222:223], s[86:87], 0, v[130:131]
	s_mov_b32 m0, s74
	v_lshl_add_u64 v[224:225], s[62:63], 0, v[132:133]
	global_load_lds_dwordx4 v[222:223], off
	v_lshl_add_u64 v[222:223], s[86:87], 0, v[134:135]
	s_mov_b32 m0, s76
	s_nop 0
	global_load_lds_dwordx4 v[222:223], off
	v_lshl_add_u64 v[222:223], s[62:63], 0, v[128:129]
	s_mov_b32 m0, s36
	s_nop 0
	global_load_lds_dwordx4 v[222:223], off
	s_mov_b32 m0, s37
	s_nop 0
	global_load_lds_dwordx4 v[224:225], off
	ds_read_b128 v[184:187], v146 offset:16384
	ds_read_b128 v[188:191], v146 offset:17408
	ds_read_b128 v[192:195], v146 offset:18432
	ds_read_b128 v[196:199], v146 offset:19456
	ds_read_b128 v[200:203], v146 offset:20480
	ds_read_b128 v[204:207], v146 offset:21504
	ds_read_b128 v[208:211], v146 offset:22528
	ds_read_b128 v[212:215], v146 offset:23552
	s_waitcnt vmcnt(8)
	s_waitcnt lgkmcnt(0)
	s_barrier
	s_setprio 1
	s_waitcnt lgkmcnt(0)
	v_mfma_f32_16x16x32_bf16 v[112:115], v[148:151], v[184:187], v[112:115]
	v_mfma_f32_16x16x32_bf16 v[116:119], v[156:159], v[184:187], v[116:119]
	v_mfma_f32_16x16x32_bf16 v[108:111], v[148:151], v[192:195], v[108:111]
	v_mfma_f32_16x16x32_bf16 v[104:107], v[156:159], v[192:195], v[104:107]
	v_mfma_f32_16x16x32_bf16 v[60:63], v[148:151], v[200:203], v[60:63]
	v_mfma_f32_16x16x32_bf16 v[56:59], v[156:159], v[200:203], v[56:59]
	v_mfma_f32_16x16x32_bf16 v[20:23], v[148:151], v[208:211], v[20:23]
	v_mfma_f32_16x16x32_bf16 v[16:19], v[156:159], v[208:211], v[16:19]
	v_mfma_f32_16x16x32_bf16 v[112:115], v[152:155], v[188:191], v[112:115]
	v_mfma_f32_16x16x32_bf16 v[116:119], v[160:163], v[188:191], v[116:119]
	v_mfma_f32_16x16x32_bf16 v[108:111], v[152:155], v[196:199], v[108:111]
	v_mfma_f32_16x16x32_bf16 v[104:107], v[160:163], v[196:199], v[104:107]
	v_mfma_f32_16x16x32_bf16 v[60:63], v[152:155], v[204:207], v[60:63]
	v_mfma_f32_16x16x32_bf16 v[56:59], v[160:163], v[204:207], v[56:59]
	v_mfma_f32_16x16x32_bf16 v[20:23], v[152:155], v[212:215], v[20:23]
	v_mfma_f32_16x16x32_bf16 v[16:19], v[160:163], v[212:215], v[16:19]
	s_setprio 0
	s_setprio 1
	v_mfma_f32_16x16x32_bf16 v[124:127], v[164:167], v[184:187], v[124:127]
	v_mfma_f32_16x16x32_bf16 v[120:123], v[172:175], v[184:187], v[120:123]
	v_mfma_f32_16x16x32_bf16 v[84:87], v[164:167], v[192:195], v[84:87]
	v_mfma_f32_16x16x32_bf16 v[80:83], v[172:175], v[192:195], v[80:83]
	v_mfma_f32_16x16x32_bf16 v[36:39], v[164:167], v[200:203], v[36:39]
	v_mfma_f32_16x16x32_bf16 v[32:35], v[172:175], v[200:203], v[32:35]
	v_mfma_f32_16x16x32_bf16 v[4:7], v[164:167], v[208:211], v[4:7]
	v_mfma_f32_16x16x32_bf16 v[0:3], v[172:175], v[208:211], v[0:3]
	v_mfma_f32_16x16x32_bf16 v[124:127], v[168:171], v[188:191], v[124:127]
	v_mfma_f32_16x16x32_bf16 v[120:123], v[180:183], v[188:191], v[120:123]
	v_mfma_f32_16x16x32_bf16 v[84:87], v[168:171], v[196:199], v[84:87]
	v_mfma_f32_16x16x32_bf16 v[80:83], v[180:183], v[196:199], v[80:83]
	v_mfma_f32_16x16x32_bf16 v[36:39], v[168:171], v[204:207], v[36:39]
	v_mfma_f32_16x16x32_bf16 v[32:35], v[180:183], v[204:207], v[32:35]
	v_mfma_f32_16x16x32_bf16 v[4:7], v[168:171], v[212:215], v[4:7]
	v_mfma_f32_16x16x32_bf16 v[0:3], v[180:183], v[212:215], v[0:3]
	s_setprio 0
	s_barrier
	s_add_u32 s62, s62, 0x80000
	s_addc_u32 s63, s63, 0
	s_mov_b32 m0, s40
	v_lshl_add_u64 v[226:227], s[62:63], 0, v[128:129]
	global_load_lds_dwordx4 v[226:227], off
	v_lshl_add_u64 v[226:227], s[62:63], 0, v[132:133]
	s_mov_b32 m0, s41
	s_nop 0
	global_load_lds_dwordx4 v[226:227], off
	ds_read_b128 v[148:151], v147
	ds_read_b128 v[152:155], v147 offset:1024
	ds_read_b128 v[156:159], v147 offset:2048
	ds_read_b128 v[160:163], v147 offset:3072
	ds_read_b128 v[164:167], v138
	ds_read_b128 v[168:171], v138 offset:1024
	ds_read_b128 v[172:175], v138 offset:2048
	ds_read_b128 v[180:183], v138 offset:3072
	ds_read_b128 v[184:187], v146 offset:32768
	ds_read_b128 v[188:191], v146 offset:33792
	ds_read_b128 v[192:195], v146 offset:34816
	ds_read_b128 v[196:199], v146 offset:35840
	ds_read_b128 v[200:203], v146 offset:36864
	ds_read_b128 v[204:207], v146 offset:37888
	ds_read_b128 v[208:211], v146 offset:38912
	ds_read_b128 v[212:215], v146 offset:39936
	s_waitcnt vmcnt(8)
	s_waitcnt lgkmcnt(0)
	s_barrier
	s_setprio 1
	s_waitcnt lgkmcnt(0)
	v_mfma_f32_16x16x32_bf16 v[8:11], v[148:151], v[184:187], v[8:11]
	v_mfma_f32_16x16x32_bf16 v[12:15], v[156:159], v[184:187], v[12:15]
	v_mfma_f32_16x16x32_bf16 v[40:43], v[148:151], v[192:195], v[40:43]
	v_mfma_f32_16x16x32_bf16 v[44:47], v[156:159], v[192:195], v[44:47]
	v_mfma_f32_16x16x32_bf16 v[64:67], v[148:151], v[200:203], v[64:67]
	v_mfma_f32_16x16x32_bf16 v[68:71], v[156:159], v[200:203], v[68:71]
	v_mfma_f32_16x16x32_bf16 v[88:91], v[148:151], v[208:211], v[88:91]
	v_mfma_f32_16x16x32_bf16 v[92:95], v[156:159], v[208:211], v[92:95]
	v_mfma_f32_16x16x32_bf16 v[8:11], v[152:155], v[188:191], v[8:11]
	v_mfma_f32_16x16x32_bf16 v[12:15], v[160:163], v[188:191], v[12:15]
	v_mfma_f32_16x16x32_bf16 v[40:43], v[152:155], v[196:199], v[40:43]
	v_mfma_f32_16x16x32_bf16 v[44:47], v[160:163], v[196:199], v[44:47]
	v_mfma_f32_16x16x32_bf16 v[64:67], v[152:155], v[204:207], v[64:67]
	v_mfma_f32_16x16x32_bf16 v[68:71], v[160:163], v[204:207], v[68:71]
	v_mfma_f32_16x16x32_bf16 v[88:91], v[152:155], v[212:215], v[88:91]
	v_mfma_f32_16x16x32_bf16 v[92:95], v[160:163], v[212:215], v[92:95]
	s_setprio 0
	s_setprio 1
	v_mfma_f32_16x16x32_bf16 v[28:31], v[164:167], v[184:187], v[28:31]
	v_mfma_f32_16x16x32_bf16 v[24:27], v[172:175], v[184:187], v[24:27]
	v_mfma_f32_16x16x32_bf16 v[48:51], v[164:167], v[192:195], v[48:51]
	v_mfma_f32_16x16x32_bf16 v[52:55], v[172:175], v[192:195], v[52:55]
	v_mfma_f32_16x16x32_bf16 v[72:75], v[164:167], v[200:203], v[72:75]
	v_mfma_f32_16x16x32_bf16 v[76:79], v[172:175], v[200:203], v[76:79]
	v_mfma_f32_16x16x32_bf16 v[96:99], v[164:167], v[208:211], v[96:99]
	v_mfma_f32_16x16x32_bf16 v[100:103], v[172:175], v[208:211], v[100:103]
	v_mfma_f32_16x16x32_bf16 v[28:31], v[168:171], v[188:191], v[28:31]
	v_mfma_f32_16x16x32_bf16 v[24:27], v[180:183], v[188:191], v[24:27]
	v_mfma_f32_16x16x32_bf16 v[48:51], v[168:171], v[196:199], v[48:51]
	v_mfma_f32_16x16x32_bf16 v[52:55], v[180:183], v[196:199], v[52:55]
	v_mfma_f32_16x16x32_bf16 v[72:75], v[168:171], v[204:207], v[72:75]
	v_mfma_f32_16x16x32_bf16 v[76:79], v[180:183], v[204:207], v[76:79]
	v_mfma_f32_16x16x32_bf16 v[96:99], v[168:171], v[212:215], v[96:99]
	v_mfma_f32_16x16x32_bf16 v[100:103], v[180:183], v[212:215], v[100:103]
	s_setprio 0
	s_barrier
; #define PG8_BAR __builtin_amdgcn_s_barrier()
; template <class Epi>
; __device__ __forceinline__ void gemm_phase(LAS unsigned char* lds, const Gemm g, const StaticOrder& S, const Epi& E) {
;     ...
;         if (wr == 0) PG8_BAR;
	s_mov_b32 m0, s80
	v_lshl_add_u64 v[216:217], v[216:217], 0, s[22:23]
	s_add_u32 s52, s52, 0x80080
	global_load_lds_dwordx4 v[216:217], off
	v_lshl_add_u64 v[216:217], v[218:219], 0, s[22:23]
	s_mov_b32 m0, s81
	s_addc_u32 s53, s53, 0
	global_load_lds_dwordx4 v[216:217], off
	v_lshl_add_u64 v[216:217], s[52:53], 0, v[130:131]
	s_mov_b32 m0, s82
	s_nop 0
	global_load_lds_dwordx4 v[216:217], off
	v_lshl_add_u64 v[216:217], s[52:53], 0, v[134:135]
	s_mov_b32 m0, s83
	s_nop 0
	global_load_lds_dwordx4 v[216:217], off
	v_lshl_add_u64 v[216:217], v[222:223], 0, s[22:23]
	s_mov_b32 m0, s43
	s_nop 0
	global_load_lds_dwordx4 v[216:217], off
	v_lshl_add_u64 v[216:217], v[224:225], 0, s[22:23]
	s_mov_b32 m0, s64
	s_nop 0
	global_load_lds_dwordx4 v[216:217], off
	ds_read_b128 v[184:187], v146 offset:49152
	ds_read_b128 v[188:191], v146 offset:50176
	ds_read_b128 v[192:195], v146 offset:51200
	ds_read_b128 v[196:199], v146 offset:52224
	ds_read_b128 v[200:203], v146 offset:53248
	ds_read_b128 v[204:207], v146 offset:54272
	ds_read_b128 v[208:211], v146 offset:55296
	ds_read_b128 v[212:215], v146 offset:56320
	s_waitcnt vmcnt(8)
	s_waitcnt lgkmcnt(0)
	s_barrier
	s_setprio 1
	s_waitcnt lgkmcnt(0)
	v_mfma_f32_16x16x32_bf16 v[112:115], v[148:151], v[184:187], v[112:115]
	v_mfma_f32_16x16x32_bf16 v[116:119], v[156:159], v[184:187], v[116:119]
	v_mfma_f32_16x16x32_bf16 v[108:111], v[148:151], v[192:195], v[108:111]
	v_mfma_f32_16x16x32_bf16 v[104:107], v[156:159], v[192:195], v[104:107]
	v_mfma_f32_16x16x32_bf16 v[60:63], v[148:151], v[200:203], v[60:63]
	v_mfma_f32_16x16x32_bf16 v[56:59], v[156:159], v[200:203], v[56:59]
	v_mfma_f32_16x16x32_bf16 v[20:23], v[148:151], v[208:211], v[20:23]
	v_mfma_f32_16x16x32_bf16 v[16:19], v[156:159], v[208:211], v[16:19]
	v_mfma_f32_16x16x32_bf16 v[112:115], v[152:155], v[188:191], v[112:115]
	v_mfma_f32_16x16x32_bf16 v[116:119], v[160:163], v[188:191], v[116:119]
	v_mfma_f32_16x16x32_bf16 v[108:111], v[152:155], v[196:199], v[108:111]
	v_mfma_f32_16x16x32_bf16 v[104:107], v[160:163], v[196:199], v[104:107]
	v_mfma_f32_16x16x32_bf16 v[60:63], v[152:155], v[204:207], v[60:63]
	v_mfma_f32_16x16x32_bf16 v[56:59], v[160:163], v[204:207], v[56:59]
	v_mfma_f32_16x16x32_bf16 v[20:23], v[152:155], v[212:215], v[20:23]
	v_mfma_f32_16x16x32_bf16 v[16:19], v[160:163], v[212:215], v[16:19]
	s_setprio 0
	s_setprio 1
	v_mfma_f32_16x16x32_bf16 v[124:127], v[164:167], v[184:187], v[124:127]
	v_mfma_f32_16x16x32_bf16 v[120:123], v[172:175], v[184:187], v[120:123]
	v_mfma_f32_16x16x32_bf16 v[84:87], v[164:167], v[192:195], v[84:87]
	v_mfma_f32_16x16x32_bf16 v[80:83], v[172:175], v[192:195], v[80:83]
	v_mfma_f32_16x16x32_bf16 v[36:39], v[164:167], v[200:203], v[36:39]
	v_mfma_f32_16x16x32_bf16 v[32:35], v[172:175], v[200:203], v[32:35]
	v_mfma_f32_16x16x32_bf16 v[4:7], v[164:167], v[208:211], v[4:7]
	v_mfma_f32_16x16x32_bf16 v[0:3], v[172:175], v[208:211], v[0:3]
	v_mfma_f32_16x16x32_bf16 v[124:127], v[168:171], v[188:191], v[124:127]
	v_mfma_f32_16x16x32_bf16 v[120:123], v[180:183], v[188:191], v[120:123]
	v_mfma_f32_16x16x32_bf16 v[84:87], v[168:171], v[196:199], v[84:87]
	v_mfma_f32_16x16x32_bf16 v[80:83], v[180:183], v[196:199], v[80:83]
	v_mfma_f32_16x16x32_bf16 v[36:39], v[168:171], v[204:207], v[36:39]
	v_mfma_f32_16x16x32_bf16 v[32:35], v[180:183], v[204:207], v[32:35]
	v_mfma_f32_16x16x32_bf16 v[4:7], v[168:171], v[212:215], v[4:7]
	v_mfma_f32_16x16x32_bf16 v[0:3], v[180:183], v[212:215], v[0:3]
	s_setprio 0
	s_barrier
	s_add_i32 s85, s85, 2
	s_add_u32 s79, s79, 0x100
	s_addc_u32 s84, s84, 0
	s_add_u32 s50, s50, 0x100
	s_addc_u32 s51, s51, 0
	s_cmp_gt_u32 s85, 13
	s_cbranch_scc0 .LBB0_705
	s_and_b64 vcc, exec, s[26:27]
	s_cbranch_vccz .LBB0_708
	s_barrier

.LBB0_807:
	s_add_u32 s34, s60, 0xfff80080
	s_addc_u32 s35, s61, -1
	s_cmp_eq_u32 s74, 28
	s_cselect_b32 s65, s51, s35
	s_cselect_b32 s64, s57, s34
	s_cselect_b32 s63, s49, s73
	s_cselect_b32 s62, s67, s72
	v_lshl_add_u64 v[216:217], s[60:61], 0, v[128:129]
	s_add_i32 m0, s15, 0xc000
	s_nop 0
	global_load_lds_dwordx4 v[216:217], off
	v_lshl_add_u64 v[216:217], s[60:61], 0, v[132:133]
	s_add_i32 m0, s15, 0xe000
	s_nop 0
	global_load_lds_dwordx4 v[216:217], off
	ds_read_b128 v[138:141], v148
	ds_read_b128 v[152:155], v148 offset:1024
	ds_read_b128 v[156:159], v148 offset:2048
	ds_read_b128 v[160:163], v148 offset:3072
	ds_read_b128 v[164:167], v149
	ds_read_b128 v[168:171], v149 offset:1024
	ds_read_b128 v[172:175], v149 offset:2048
	ds_read_b128 v[180:183], v149 offset:3072
	ds_read_b128 v[184:187], v150
	ds_read_b128 v[188:191], v150 offset:1024
	ds_read_b128 v[192:195], v150 offset:2048
	ds_read_b128 v[196:199], v150 offset:3072
	ds_read_b128 v[200:203], v150 offset:4096
	ds_read_b128 v[204:207], v150 offset:5120
	ds_read_b128 v[208:211], v150 offset:6144
	ds_read_b128 v[212:215], v150 offset:7168
	s_waitcnt vmcnt(8)
	s_waitcnt lgkmcnt(0)
	s_barrier
	s_setprio 1
	s_waitcnt lgkmcnt(0)
	v_mfma_f32_16x16x32_bf16 v[124:127], v[138:141], v[184:187], v[124:127]
	v_mfma_f32_16x16x32_bf16 v[120:123], v[156:159], v[184:187], v[120:123]
	v_mfma_f32_16x16x32_bf16 v[108:111], v[138:141], v[192:195], v[108:111]
	v_mfma_f32_16x16x32_bf16 v[104:107], v[156:159], v[192:195], v[104:107]
	v_mfma_f32_16x16x32_bf16 v[92:95], v[138:141], v[200:203], v[92:95]
	v_mfma_f32_16x16x32_bf16 v[88:91], v[156:159], v[200:203], v[88:91]
	v_mfma_f32_16x16x32_bf16 v[76:79], v[138:141], v[208:211], v[76:79]
	v_mfma_f32_16x16x32_bf16 v[72:75], v[156:159], v[208:211], v[72:75]
	v_mfma_f32_16x16x32_bf16 v[124:127], v[152:155], v[188:191], v[124:127]
	v_mfma_f32_16x16x32_bf16 v[120:123], v[160:163], v[188:191], v[120:123]
	v_mfma_f32_16x16x32_bf16 v[108:111], v[152:155], v[196:199], v[108:111]
	v_mfma_f32_16x16x32_bf16 v[104:107], v[160:163], v[196:199], v[104:107]
	v_mfma_f32_16x16x32_bf16 v[92:95], v[152:155], v[204:207], v[92:95]
	v_mfma_f32_16x16x32_bf16 v[88:91], v[160:163], v[204:207], v[88:91]
	v_mfma_f32_16x16x32_bf16 v[76:79], v[152:155], v[212:215], v[76:79]
	v_mfma_f32_16x16x32_bf16 v[72:75], v[160:163], v[212:215], v[72:75]
	s_setprio 0
	s_setprio 1
	v_mfma_f32_16x16x32_bf16 v[116:119], v[164:167], v[184:187], v[116:119]
	v_mfma_f32_16x16x32_bf16 v[112:115], v[172:175], v[184:187], v[112:115]
	v_mfma_f32_16x16x32_bf16 v[100:103], v[164:167], v[192:195], v[100:103]
	v_mfma_f32_16x16x32_bf16 v[96:99], v[172:175], v[192:195], v[96:99]
	v_mfma_f32_16x16x32_bf16 v[84:87], v[164:167], v[200:203], v[84:87]
	v_mfma_f32_16x16x32_bf16 v[80:83], v[172:175], v[200:203], v[80:83]
	v_mfma_f32_16x16x32_bf16 v[68:71], v[164:167], v[208:211], v[68:71]
	v_mfma_f32_16x16x32_bf16 v[64:67], v[172:175], v[208:211], v[64:67]
	v_mfma_f32_16x16x32_bf16 v[116:119], v[168:171], v[188:191], v[116:119]
	v_mfma_f32_16x16x32_bf16 v[112:115], v[180:183], v[188:191], v[112:115]
	v_mfma_f32_16x16x32_bf16 v[100:103], v[168:171], v[196:199], v[100:103]
	v_mfma_f32_16x16x32_bf16 v[96:99], v[180:183], v[196:199], v[96:99]
	v_mfma_f32_16x16x32_bf16 v[84:87], v[168:171], v[204:207], v[84:87]
	v_mfma_f32_16x16x32_bf16 v[80:83], v[180:183], v[204:207], v[80:83]
	v_mfma_f32_16x16x32_bf16 v[68:71], v[168:171], v[212:215], v[68:71]
	v_mfma_f32_16x16x32_bf16 v[64:67], v[180:183], v[212:215], v[64:67]
	s_setprio 0
	s_barrier
	s_add_i32 s34, s59, s14
	v_lshl_add_u64 v[216:217], s[62:63], 0, v[130:131]
	s_mov_b32 m0, s34
	s_nop 0
	global_load_lds_dwordx4 v[216:217], off
	s_add_i32 m0, s34, 0x2000
	s_add_u32 s34, s62, 0x80000
	v_lshl_add_u64 v[218:219], s[62:63], 0, v[134:135]
	s_addc_u32 s35, s63, 0
	s_add_i32 s75, s66, s14
	global_load_lds_dwordx4 v[218:219], off
	v_lshl_add_u64 v[222:223], s[34:35], 0, v[130:131]
	s_mov_b32 m0, s75
	v_lshl_add_u64 v[224:225], s[64:65], 0, v[132:133]
	global_load_lds_dwordx4 v[222:223], off
	v_lshl_add_u64 v[222:223], s[34:35], 0, v[134:135]
	s_add_i32 m0, s75, 0x2000
	s_nop 0
	global_load_lds_dwordx4 v[222:223], off
	v_lshl_add_u64 v[222:223], s[64:65], 0, v[128:129]
	s_mov_b32 m0, s15
	s_nop 0
	global_load_lds_dwordx4 v[222:223], off
	s_mov_b32 m0, s33
	s_nop 0
	global_load_lds_dwordx4 v[224:225], off
	ds_read_b128 v[184:187], v150 offset:16384
	ds_read_b128 v[188:191], v150 offset:17408
	ds_read_b128 v[192:195], v150 offset:18432
	ds_read_b128 v[196:199], v150 offset:19456
	ds_read_b128 v[200:203], v150 offset:20480
	ds_read_b128 v[204:207], v150 offset:21504
	ds_read_b128 v[208:211], v150 offset:22528
	ds_read_b128 v[212:215], v150 offset:23552
	s_waitcnt vmcnt(8)
	s_waitcnt lgkmcnt(0)
	s_barrier
	s_setprio 1
	s_waitcnt lgkmcnt(0)
	v_mfma_f32_16x16x32_bf16 v[60:63], v[138:141], v[184:187], v[60:63]
	v_mfma_f32_16x16x32_bf16 v[56:59], v[156:159], v[184:187], v[56:59]
	v_mfma_f32_16x16x32_bf16 v[44:47], v[138:141], v[192:195], v[44:47]
	v_mfma_f32_16x16x32_bf16 v[40:43], v[156:159], v[192:195], v[40:43]
	v_mfma_f32_16x16x32_bf16 v[28:31], v[138:141], v[200:203], v[28:31]
	v_mfma_f32_16x16x32_bf16 v[24:27], v[156:159], v[200:203], v[24:27]
	v_mfma_f32_16x16x32_bf16 v[12:15], v[138:141], v[208:211], v[12:15]
	v_mfma_f32_16x16x32_bf16 v[8:11], v[156:159], v[208:211], v[8:11]
	v_mfma_f32_16x16x32_bf16 v[60:63], v[152:155], v[188:191], v[60:63]
	v_mfma_f32_16x16x32_bf16 v[56:59], v[160:163], v[188:191], v[56:59]
	v_mfma_f32_16x16x32_bf16 v[44:47], v[152:155], v[196:199], v[44:47]
	v_mfma_f32_16x16x32_bf16 v[40:43], v[160:163], v[196:199], v[40:43]
	v_mfma_f32_16x16x32_bf16 v[28:31], v[152:155], v[204:207], v[28:31]
	v_mfma_f32_16x16x32_bf16 v[24:27], v[160:163], v[204:207], v[24:27]
	v_mfma_f32_16x16x32_bf16 v[12:15], v[152:155], v[212:215], v[12:15]
	v_mfma_f32_16x16x32_bf16 v[8:11], v[160:163], v[212:215], v[8:11]
	s_setprio 0
	s_setprio 1
	v_mfma_f32_16x16x32_bf16 v[52:55], v[164:167], v[184:187], v[52:55]
	v_mfma_f32_16x16x32_bf16 v[48:51], v[172:175], v[184:187], v[48:51]
	v_mfma_f32_16x16x32_bf16 v[36:39], v[164:167], v[192:195], v[36:39]
	v_mfma_f32_16x16x32_bf16 v[32:35], v[172:175], v[192:195], v[32:35]
	v_mfma_f32_16x16x32_bf16 v[20:23], v[164:167], v[200:203], v[20:23]
	v_mfma_f32_16x16x32_bf16 v[16:19], v[172:175], v[200:203], v[16:19]
	v_mfma_f32_16x16x32_bf16 v[4:7], v[164:167], v[208:211], v[4:7]
	v_mfma_f32_16x16x32_bf16 v[0:3], v[172:175], v[208:211], v[0:3]
	v_mfma_f32_16x16x32_bf16 v[52:55], v[168:171], v[188:191], v[52:55]
	v_mfma_f32_16x16x32_bf16 v[48:51], v[180:183], v[188:191], v[48:51]
	v_mfma_f32_16x16x32_bf16 v[36:39], v[168:171], v[196:199], v[36:39]
	v_mfma_f32_16x16x32_bf16 v[32:35], v[180:183], v[196:199], v[32:35]
	v_mfma_f32_16x16x32_bf16 v[20:23], v[168:171], v[204:207], v[20:23]
	v_mfma_f32_16x16x32_bf16 v[16:19], v[180:183], v[204:207], v[16:19]
	v_mfma_f32_16x16x32_bf16 v[4:7], v[168:171], v[212:215], v[4:7]
	v_mfma_f32_16x16x32_bf16 v[0:3], v[180:183], v[212:215], v[0:3]
	s_setprio 0
	s_barrier
	s_add_i32 s75, 0, 0x18000
	s_add_i32 s76, 0, 0x1c000
	s_add_u32 s34, s64, 0x80000
	s_addc_u32 s35, s65, 0
	s_mov_b32 m0, s36
	v_lshl_add_u64 v[226:227], s[34:35], 0, v[128:129]
	global_load_lds_dwordx4 v[226:227], off
	v_lshl_add_u64 v[226:227], s[34:35], 0, v[132:133]
	s_mov_b32 m0, s37
	s_nop 0
	global_load_lds_dwordx4 v[226:227], off
	v_add_u32_e32 v160, s75, v143
	v_add_u32_e32 v177, s76, v143
	ds_read_b128 v[138:141], v160
	ds_read_b128 v[152:155], v160 offset:1024
	ds_read_b128 v[156:159], v160 offset:2048
	ds_read_b128 v[160:163], v160 offset:3072
	ds_read_b128 v[164:167], v177
	ds_read_b128 v[168:171], v177 offset:1024
	ds_read_b128 v[172:175], v177 offset:2048
	ds_read_b128 v[180:183], v177 offset:3072
	ds_read_b128 v[184:187], v150 offset:32768
	ds_read_b128 v[188:191], v150 offset:33792
	ds_read_b128 v[192:195], v150 offset:34816
	ds_read_b128 v[196:199], v150 offset:35840
	ds_read_b128 v[200:203], v150 offset:36864
	ds_read_b128 v[204:207], v150 offset:37888
	ds_read_b128 v[208:211], v150 offset:38912
	ds_read_b128 v[212:215], v150 offset:39936
	s_waitcnt vmcnt(8)
	s_waitcnt lgkmcnt(0)
	s_barrier
	s_setprio 1
	s_waitcnt lgkmcnt(0)
	v_mfma_f32_16x16x32_bf16 v[124:127], v[138:141], v[184:187], v[124:127]
	v_mfma_f32_16x16x32_bf16 v[120:123], v[156:159], v[184:187], v[120:123]
	v_mfma_f32_16x16x32_bf16 v[108:111], v[138:141], v[192:195], v[108:111]
	v_mfma_f32_16x16x32_bf16 v[104:107], v[156:159], v[192:195], v[104:107]
	v_mfma_f32_16x16x32_bf16 v[92:95], v[138:141], v[200:203], v[92:95]
	v_mfma_f32_16x16x32_bf16 v[88:91], v[156:159], v[200:203], v[88:91]
	v_mfma_f32_16x16x32_bf16 v[76:79], v[138:141], v[208:211], v[76:79]
	v_mfma_f32_16x16x32_bf16 v[72:75], v[156:159], v[208:211], v[72:75]
	v_mfma_f32_16x16x32_bf16 v[124:127], v[152:155], v[188:191], v[124:127]
	v_mfma_f32_16x16x32_bf16 v[120:123], v[160:163], v[188:191], v[120:123]
	v_mfma_f32_16x16x32_bf16 v[108:111], v[152:155], v[196:199], v[108:111]
	v_mfma_f32_16x16x32_bf16 v[104:107], v[160:163], v[196:199], v[104:107]
	v_mfma_f32_16x16x32_bf16 v[92:95], v[152:155], v[204:207], v[92:95]
	v_mfma_f32_16x16x32_bf16 v[88:91], v[160:163], v[204:207], v[88:91]
	v_mfma_f32_16x16x32_bf16 v[76:79], v[152:155], v[212:215], v[76:79]
	v_mfma_f32_16x16x32_bf16 v[72:75], v[160:163], v[212:215], v[72:75]
	s_setprio 0
	s_setprio 1
	v_mfma_f32_16x16x32_bf16 v[116:119], v[164:167], v[184:187], v[116:119]
	v_mfma_f32_16x16x32_bf16 v[112:115], v[172:175], v[184:187], v[112:115]
	v_mfma_f32_16x16x32_bf16 v[100:103], v[164:167], v[192:195], v[100:103]
	v_mfma_f32_16x16x32_bf16 v[96:99], v[172:175], v[192:195], v[96:99]
	v_mfma_f32_16x16x32_bf16 v[84:87], v[164:167], v[200:203], v[84:87]
	v_mfma_f32_16x16x32_bf16 v[80:83], v[172:175], v[200:203], v[80:83]
	v_mfma_f32_16x16x32_bf16 v[68:71], v[164:167], v[208:211], v[68:71]
	v_mfma_f32_16x16x32_bf16 v[64:67], v[172:175], v[208:211], v[64:67]
	v_mfma_f32_16x16x32_bf16 v[116:119], v[168:171], v[188:191], v[116:119]
	v_mfma_f32_16x16x32_bf16 v[112:115], v[180:183], v[188:191], v[112:115]
	v_mfma_f32_16x16x32_bf16 v[100:103], v[168:171], v[196:199], v[100:103]
	v_mfma_f32_16x16x32_bf16 v[96:99], v[180:183], v[196:199], v[96:99]
	v_mfma_f32_16x16x32_bf16 v[84:87], v[168:171], v[204:207], v[84:87]
	v_mfma_f32_16x16x32_bf16 v[80:83], v[180:183], v[204:207], v[80:83]
	v_mfma_f32_16x16x32_bf16 v[68:71], v[168:171], v[212:215], v[68:71]
	v_mfma_f32_16x16x32_bf16 v[64:67], v[180:183], v[212:215], v[64:67]
	s_setprio 0
	s_barrier
; #define PG8_BAR __builtin_amdgcn_s_barrier()
; template <class Epi>
; __device__ __forceinline__ void gemm_phase(LAS unsigned char* lds, const Gemm g, const StaticOrder& S, const Epi& E) {
;     ...
;         if (wr == 0) PG8_BAR;
	s_add_i32 s34, s75, s14
	v_lshl_add_u64 v[216:217], v[216:217], 0, s[20:21]
	s_mov_b32 m0, s34
	s_nop 0
	global_load_lds_dwordx4 v[216:217], off
	s_add_i32 m0, s34, 0x2000
	s_add_u32 s34, s62, 0x80080
	v_lshl_add_u64 v[216:217], v[218:219], 0, s[20:21]
	s_addc_u32 s35, s63, 0
	s_add_i32 s62, s76, s14
	global_load_lds_dwordx4 v[216:217], off
	v_lshl_add_u64 v[216:217], s[34:35], 0, v[130:131]
	s_mov_b32 m0, s62
	s_nop 0
	global_load_lds_dwordx4 v[216:217], off
	v_lshl_add_u64 v[216:217], s[34:35], 0, v[134:135]
	s_add_i32 m0, s62, 0x2000
	s_nop 0
	global_load_lds_dwordx4 v[216:217], off
	v_lshl_add_u64 v[216:217], v[222:223], 0, s[20:21]
	s_mov_b32 m0, s40
	s_nop 0
	global_load_lds_dwordx4 v[216:217], off
	v_lshl_add_u64 v[216:217], v[224:225], 0, s[20:21]
	s_mov_b32 m0, s41
	s_nop 0
	global_load_lds_dwordx4 v[216:217], off
	ds_read_b128 v[184:187], v150 offset:49152
	ds_read_b128 v[188:191], v150 offset:50176
	ds_read_b128 v[192:195], v150 offset:51200
	ds_read_b128 v[196:199], v150 offset:52224
	ds_read_b128 v[200:203], v150 offset:53248
	ds_read_b128 v[204:207], v150 offset:54272
	ds_read_b128 v[208:211], v150 offset:55296
	ds_read_b128 v[212:215], v150 offset:56320
	s_waitcnt vmcnt(8)
	s_waitcnt lgkmcnt(0)
	s_barrier
	s_setprio 1
	s_waitcnt lgkmcnt(0)
	v_mfma_f32_16x16x32_bf16 v[60:63], v[138:141], v[184:187], v[60:63]
	v_mfma_f32_16x16x32_bf16 v[56:59], v[156:159], v[184:187], v[56:59]
	v_mfma_f32_16x16x32_bf16 v[44:47], v[138:141], v[192:195], v[44:47]
	v_mfma_f32_16x16x32_bf16 v[40:43], v[156:159], v[192:195], v[40:43]
	v_mfma_f32_16x16x32_bf16 v[28:31], v[138:141], v[200:203], v[28:31]
	v_mfma_f32_16x16x32_bf16 v[24:27], v[156:159], v[200:203], v[24:27]
	v_mfma_f32_16x16x32_bf16 v[12:15], v[138:141], v[208:211], v[12:15]
	v_mfma_f32_16x16x32_bf16 v[8:11], v[156:159], v[208:211], v[8:11]
	v_mfma_f32_16x16x32_bf16 v[60:63], v[152:155], v[188:191], v[60:63]
	v_mfma_f32_16x16x32_bf16 v[56:59], v[160:163], v[188:191], v[56:59]
	v_mfma_f32_16x16x32_bf16 v[44:47], v[152:155], v[196:199], v[44:47]
	v_mfma_f32_16x16x32_bf16 v[40:43], v[160:163], v[196:199], v[40:43]
	v_mfma_f32_16x16x32_bf16 v[28:31], v[152:155], v[204:207], v[28:31]
	v_mfma_f32_16x16x32_bf16 v[24:27], v[160:163], v[204:207], v[24:27]
	v_mfma_f32_16x16x32_bf16 v[12:15], v[152:155], v[212:215], v[12:15]
	v_mfma_f32_16x16x32_bf16 v[8:11], v[160:163], v[212:215], v[8:11]
	s_setprio 0
	s_setprio 1
	v_mfma_f32_16x16x32_bf16 v[52:55], v[164:167], v[184:187], v[52:55]
	v_mfma_f32_16x16x32_bf16 v[48:51], v[172:175], v[184:187], v[48:51]
	v_mfma_f32_16x16x32_bf16 v[36:39], v[164:167], v[192:195], v[36:39]
	v_mfma_f32_16x16x32_bf16 v[32:35], v[172:175], v[192:195], v[32:35]
	v_mfma_f32_16x16x32_bf16 v[20:23], v[164:167], v[200:203], v[20:23]
	v_mfma_f32_16x16x32_bf16 v[16:19], v[172:175], v[200:203], v[16:19]
	v_mfma_f32_16x16x32_bf16 v[4:7], v[164:167], v[208:211], v[4:7]
	v_mfma_f32_16x16x32_bf16 v[0:3], v[172:175], v[208:211], v[0:3]
	v_mfma_f32_16x16x32_bf16 v[52:55], v[168:171], v[188:191], v[52:55]
	v_mfma_f32_16x16x32_bf16 v[48:51], v[180:183], v[188:191], v[48:51]
	v_mfma_f32_16x16x32_bf16 v[36:39], v[168:171], v[196:199], v[36:39]
	v_mfma_f32_16x16x32_bf16 v[32:35], v[180:183], v[196:199], v[32:35]
	v_mfma_f32_16x16x32_bf16 v[20:23], v[168:171], v[204:207], v[20:23]
	v_mfma_f32_16x16x32_bf16 v[16:19], v[180:183], v[204:207], v[16:19]
	v_mfma_f32_16x16x32_bf16 v[4:7], v[168:171], v[212:215], v[4:7]
	v_mfma_f32_16x16x32_bf16 v[0:3], v[180:183], v[212:215], v[0:3]
	s_setprio 0
	s_barrier
	s_add_i32 s74, s74, 2
	s_add_u32 s60, s60, 0x100
	s_addc_u32 s61, s61, 0
	s_add_u32 s72, s72, 0x100
	s_addc_u32 s73, s73, 0
	s_cmp_gt_u32 s74, 29
	s_cbranch_scc0 .LBB0_807
	s_and_b64 vcc, exec, s[26:27]
	s_cbranch_vccz .LBB0_810
	s_barrier

.LBB0_896:
	s_add_u32 s34, s10, 0xfff80080
	s_addc_u32 s35, s11, -1
	s_cmp_eq_u32 s73, 28
	s_cselect_b32 s77, s1, s35
	s_cselect_b32 s76, s9, s34
	s_cselect_b32 s75, s41, s72
	s_cselect_b32 s74, s65, s67
	v_lshl_add_u64 v[120:121], s[10:11], 0, v[170:171]
	s_add_i32 m0, s90, 0xc000
	s_nop 0
	global_load_lds_dwordx4 v[120:121], off
	v_lshl_add_u64 v[120:121], s[10:11], 0, v[172:173]
	s_add_i32 m0, s90, 0xe000
	s_nop 0
	global_load_lds_dwordx4 v[120:121], off
	ds_read_b128 v[130:133], v230
	ds_read_b128 v[134:137], v230 offset:1024
	ds_read_b128 v[138:141], v230 offset:2048
	ds_read_b128 v[142:145], v230 offset:3072
	ds_read_b128 v[146:149], v231
	ds_read_b128 v[150:153], v231 offset:1024
	ds_read_b128 v[154:157], v231 offset:2048
	ds_read_b128 v[158:161], v231 offset:3072
	ds_read_b128 v[182:185], v232
	ds_read_b128 v[186:189], v232 offset:1024
	ds_read_b128 v[190:193], v232 offset:2048
	ds_read_b128 v[194:197], v232 offset:3072
	ds_read_b128 v[198:201], v232 offset:4096
	ds_read_b128 v[202:205], v232 offset:5120
	ds_read_b128 v[206:209], v232 offset:6144
	ds_read_b128 v[210:213], v232 offset:7168
	s_waitcnt vmcnt(8)
	s_waitcnt lgkmcnt(0)
	s_barrier
	s_setprio 1
	s_waitcnt lgkmcnt(0)
	v_mfma_f32_16x16x32_bf16 v[126:129], v[130:133], v[182:185], v[126:129]
	v_mfma_f32_16x16x32_bf16 v[92:95], v[138:141], v[182:185], v[92:95]
	v_mfma_f32_16x16x32_bf16 v[108:111], v[130:133], v[190:193], v[108:111]
	v_mfma_f32_16x16x32_bf16 v[68:71], v[138:141], v[190:193], v[68:71]
	v_mfma_f32_16x16x32_bf16 v[100:103], v[130:133], v[198:201], v[100:103]
	v_mfma_f32_16x16x32_bf16 v[64:67], v[138:141], v[198:201], v[64:67]
	v_mfma_f32_16x16x32_bf16 v[116:119], v[130:133], v[206:209], v[116:119]
	v_mfma_f32_16x16x32_bf16 v[84:87], v[138:141], v[206:209], v[84:87]
	v_mfma_f32_16x16x32_bf16 v[126:129], v[134:137], v[186:189], v[126:129]
	v_mfma_f32_16x16x32_bf16 v[92:95], v[142:145], v[186:189], v[92:95]
	v_mfma_f32_16x16x32_bf16 v[108:111], v[134:137], v[194:197], v[108:111]
	v_mfma_f32_16x16x32_bf16 v[68:71], v[142:145], v[194:197], v[68:71]
	v_mfma_f32_16x16x32_bf16 v[100:103], v[134:137], v[202:205], v[100:103]
	v_mfma_f32_16x16x32_bf16 v[64:67], v[142:145], v[202:205], v[64:67]
	v_mfma_f32_16x16x32_bf16 v[116:119], v[134:137], v[210:213], v[116:119]
	v_mfma_f32_16x16x32_bf16 v[84:87], v[142:145], v[210:213], v[84:87]
	s_setprio 0
	s_setprio 1
	v_mfma_f32_16x16x32_bf16 v[120:123], v[146:149], v[182:185], v[122:125]
	v_mfma_f32_16x16x32_bf16 v[88:91], v[154:157], v[182:185], v[88:91]
	v_mfma_f32_16x16x32_bf16 v[104:107], v[146:149], v[190:193], v[104:107]
	v_mfma_f32_16x16x32_bf16 v[60:63], v[154:157], v[190:193], v[60:63]
	v_mfma_f32_16x16x32_bf16 v[96:99], v[146:149], v[198:201], v[96:99]
	v_mfma_f32_16x16x32_bf16 v[56:59], v[154:157], v[198:201], v[56:59]
	v_mfma_f32_16x16x32_bf16 v[112:115], v[146:149], v[206:209], v[112:115]
	v_mfma_f32_16x16x32_bf16 v[80:83], v[154:157], v[206:209], v[80:83]
	v_mfma_f32_16x16x32_bf16 v[120:123], v[150:153], v[186:189], v[120:123]
	v_mfma_f32_16x16x32_bf16 v[88:91], v[158:161], v[186:189], v[88:91]
	v_mfma_f32_16x16x32_bf16 v[104:107], v[150:153], v[194:197], v[104:107]
	v_mfma_f32_16x16x32_bf16 v[60:63], v[158:161], v[194:197], v[60:63]
	v_mfma_f32_16x16x32_bf16 v[96:99], v[150:153], v[202:205], v[96:99]
	v_mfma_f32_16x16x32_bf16 v[56:59], v[158:161], v[202:205], v[56:59]
	v_mfma_f32_16x16x32_bf16 v[112:115], v[150:153], v[210:213], v[112:115]
	v_mfma_f32_16x16x32_bf16 v[80:83], v[158:161], v[210:213], v[80:83]
	s_setprio 0
	s_barrier
	s_add_i32 s34, s37, s89
	v_lshl_add_u64 v[214:215], s[74:75], 0, v[164:165]
	s_mov_b32 m0, s34
	s_nop 0
	global_load_lds_dwordx4 v[214:215], off
	s_add_i32 m0, s34, 0x2000
	s_add_u32 s34, s74, 0x80000
	v_lshl_add_u64 v[216:217], s[74:75], 0, v[168:169]
	s_addc_u32 s35, s75, 0
	s_add_i32 s78, s38, s89
	global_load_lds_dwordx4 v[216:217], off
	v_lshl_add_u64 v[124:125], s[34:35], 0, v[164:165]
	s_mov_b32 m0, s78
	v_lshl_add_u64 v[218:219], s[76:77], 0, v[162:163]
	global_load_lds_dwordx4 v[124:125], off
	v_lshl_add_u64 v[124:125], s[34:35], 0, v[168:169]
	s_add_i32 m0, s78, 0x2000
	v_lshl_add_u64 v[234:235], s[76:77], 0, v[166:167]
	global_load_lds_dwordx4 v[124:125], off
	s_mov_b32 m0, s90
	s_nop 0
	global_load_lds_dwordx4 v[218:219], off
	s_mov_b32 m0, s91
	s_nop 0
	global_load_lds_dwordx4 v[234:235], off
	ds_read_b128 v[182:185], v232 offset:16384
	ds_read_b128 v[186:189], v232 offset:17408
	ds_read_b128 v[190:193], v232 offset:18432
	ds_read_b128 v[194:197], v232 offset:19456
	ds_read_b128 v[198:201], v232 offset:20480
	ds_read_b128 v[202:205], v232 offset:21504
	ds_read_b128 v[206:209], v232 offset:22528
	ds_read_b128 v[210:213], v232 offset:23552
	s_waitcnt vmcnt(8)
	s_waitcnt lgkmcnt(0)
	s_barrier
	s_setprio 1
	s_waitcnt lgkmcnt(0)
	v_mfma_f32_16x16x32_bf16 v[52:55], v[130:133], v[182:185], v[52:55]
	v_mfma_f32_16x16x32_bf16 v[20:23], v[138:141], v[182:185], v[20:23]
	v_mfma_f32_16x16x32_bf16 v[44:47], v[130:133], v[190:193], v[44:47]
	v_mfma_f32_16x16x32_bf16 v[16:19], v[138:141], v[190:193], v[16:19]
	v_mfma_f32_16x16x32_bf16 v[36:39], v[130:133], v[198:201], v[36:39]
	v_mfma_f32_16x16x32_bf16 v[12:15], v[138:141], v[198:201], v[12:15]
	v_mfma_f32_16x16x32_bf16 v[76:79], v[130:133], v[206:209], v[76:79]
	v_mfma_f32_16x16x32_bf16 v[28:31], v[138:141], v[206:209], v[28:31]
	v_mfma_f32_16x16x32_bf16 v[52:55], v[134:137], v[186:189], v[52:55]
	v_mfma_f32_16x16x32_bf16 v[20:23], v[142:145], v[186:189], v[20:23]
	v_mfma_f32_16x16x32_bf16 v[44:47], v[134:137], v[194:197], v[44:47]
	v_mfma_f32_16x16x32_bf16 v[16:19], v[142:145], v[194:197], v[16:19]
	v_mfma_f32_16x16x32_bf16 v[36:39], v[134:137], v[202:205], v[36:39]
	v_mfma_f32_16x16x32_bf16 v[12:15], v[142:145], v[202:205], v[12:15]
	v_mfma_f32_16x16x32_bf16 v[76:79], v[134:137], v[210:213], v[76:79]
	v_mfma_f32_16x16x32_bf16 v[28:31], v[142:145], v[210:213], v[28:31]
	s_setprio 0
	s_setprio 1
	v_mfma_f32_16x16x32_bf16 v[48:51], v[146:149], v[182:185], v[48:51]
	v_mfma_f32_16x16x32_bf16 v[8:11], v[154:157], v[182:185], v[8:11]
	v_mfma_f32_16x16x32_bf16 v[40:43], v[146:149], v[190:193], v[40:43]
	v_mfma_f32_16x16x32_bf16 v[4:7], v[154:157], v[190:193], v[4:7]
	v_mfma_f32_16x16x32_bf16 v[32:35], v[146:149], v[198:201], v[32:35]
	v_mfma_f32_16x16x32_bf16 v[0:3], v[154:157], v[198:201], v[0:3]
	v_mfma_f32_16x16x32_bf16 v[72:75], v[146:149], v[206:209], v[72:75]
	v_mfma_f32_16x16x32_bf16 v[24:27], v[154:157], v[206:209], v[24:27]
	v_mfma_f32_16x16x32_bf16 v[48:51], v[150:153], v[186:189], v[48:51]
	v_mfma_f32_16x16x32_bf16 v[8:11], v[158:161], v[186:189], v[8:11]
	v_mfma_f32_16x16x32_bf16 v[40:43], v[150:153], v[194:197], v[40:43]
	v_mfma_f32_16x16x32_bf16 v[4:7], v[158:161], v[194:197], v[4:7]
	v_mfma_f32_16x16x32_bf16 v[32:35], v[150:153], v[202:205], v[32:35]
	v_mfma_f32_16x16x32_bf16 v[0:3], v[158:161], v[202:205], v[0:3]
	v_mfma_f32_16x16x32_bf16 v[72:75], v[150:153], v[210:213], v[72:75]
	v_mfma_f32_16x16x32_bf16 v[24:27], v[158:161], v[210:213], v[24:27]
	s_setprio 0
	s_barrier
	s_add_i32 s78, 0, 0x18000
	v_add_u32_e32 v124, s78, v223
	s_add_i32 s79, 0, 0x1c000
	ds_read_b128 v[130:133], v124
	ds_read_b128 v[134:137], v124 offset:1024
	ds_read_b128 v[138:141], v124 offset:2048
	ds_read_b128 v[142:145], v124 offset:3072
	v_add_u32_e32 v124, s79, v223
	ds_read_b128 v[146:149], v124
	ds_read_b128 v[150:153], v124 offset:1024
	ds_read_b128 v[154:157], v124 offset:2048
	ds_read_b128 v[158:161], v124 offset:3072
	s_add_u32 s34, s76, 0x80000
	s_addc_u32 s35, s77, 0
	s_mov_b32 m0, s92
	v_lshl_add_u64 v[124:125], s[34:35], 0, v[162:163]
	global_load_lds_dwordx4 v[124:125], off
	v_lshl_add_u64 v[124:125], s[34:35], 0, v[166:167]
	s_mov_b32 m0, s93
	s_nop 0
	global_load_lds_dwordx4 v[124:125], off
	ds_read_b128 v[182:185], v232 offset:32768
	ds_read_b128 v[186:189], v232 offset:33792
	ds_read_b128 v[190:193], v232 offset:34816
	ds_read_b128 v[194:197], v232 offset:35840
	ds_read_b128 v[198:201], v232 offset:36864
	ds_read_b128 v[202:205], v232 offset:37888
	ds_read_b128 v[206:209], v232 offset:38912
	ds_read_b128 v[210:213], v232 offset:39936
	s_waitcnt vmcnt(8)
	s_waitcnt lgkmcnt(0)
	s_barrier
	s_setprio 1
	s_waitcnt lgkmcnt(0)
	v_mfma_f32_16x16x32_bf16 v[124:127], v[130:133], v[182:185], v[126:129]
	v_mfma_f32_16x16x32_bf16 v[92:95], v[138:141], v[182:185], v[92:95]
	v_mfma_f32_16x16x32_bf16 v[108:111], v[130:133], v[190:193], v[108:111]
	v_mfma_f32_16x16x32_bf16 v[68:71], v[138:141], v[190:193], v[68:71]
	v_mfma_f32_16x16x32_bf16 v[100:103], v[130:133], v[198:201], v[100:103]
	v_mfma_f32_16x16x32_bf16 v[64:67], v[138:141], v[198:201], v[64:67]
	v_mfma_f32_16x16x32_bf16 v[116:119], v[130:133], v[206:209], v[116:119]
	v_mfma_f32_16x16x32_bf16 v[84:87], v[138:141], v[206:209], v[84:87]
	v_mfma_f32_16x16x32_bf16 v[126:129], v[134:137], v[186:189], v[124:127]
	v_mfma_f32_16x16x32_bf16 v[92:95], v[142:145], v[186:189], v[92:95]
	v_mfma_f32_16x16x32_bf16 v[108:111], v[134:137], v[194:197], v[108:111]
	v_mfma_f32_16x16x32_bf16 v[68:71], v[142:145], v[194:197], v[68:71]
	v_mfma_f32_16x16x32_bf16 v[100:103], v[134:137], v[202:205], v[100:103]
	v_mfma_f32_16x16x32_bf16 v[64:67], v[142:145], v[202:205], v[64:67]
	v_mfma_f32_16x16x32_bf16 v[116:119], v[134:137], v[210:213], v[116:119]
	v_mfma_f32_16x16x32_bf16 v[84:87], v[142:145], v[210:213], v[84:87]
	s_setprio 0
	s_setprio 1
	v_mfma_f32_16x16x32_bf16 v[120:123], v[146:149], v[182:185], v[120:123]
	v_mfma_f32_16x16x32_bf16 v[88:91], v[154:157], v[182:185], v[88:91]
	v_mfma_f32_16x16x32_bf16 v[104:107], v[146:149], v[190:193], v[104:107]
	v_mfma_f32_16x16x32_bf16 v[60:63], v[154:157], v[190:193], v[60:63]
	v_mfma_f32_16x16x32_bf16 v[96:99], v[146:149], v[198:201], v[96:99]
	v_mfma_f32_16x16x32_bf16 v[56:59], v[154:157], v[198:201], v[56:59]
	v_mfma_f32_16x16x32_bf16 v[112:115], v[146:149], v[206:209], v[112:115]
	v_mfma_f32_16x16x32_bf16 v[80:83], v[154:157], v[206:209], v[80:83]
	v_mfma_f32_16x16x32_bf16 v[122:125], v[150:153], v[186:189], v[120:123]
	v_mfma_f32_16x16x32_bf16 v[88:91], v[158:161], v[186:189], v[88:91]
	v_mfma_f32_16x16x32_bf16 v[104:107], v[150:153], v[194:197], v[104:107]
	v_mfma_f32_16x16x32_bf16 v[60:63], v[158:161], v[194:197], v[60:63]
	v_mfma_f32_16x16x32_bf16 v[96:99], v[150:153], v[202:205], v[96:99]
	v_mfma_f32_16x16x32_bf16 v[56:59], v[158:161], v[202:205], v[56:59]
	v_mfma_f32_16x16x32_bf16 v[112:115], v[150:153], v[210:213], v[112:115]
	v_mfma_f32_16x16x32_bf16 v[80:83], v[158:161], v[210:213], v[80:83]
	s_setprio 0
	s_barrier
; #define PG8_BAR __builtin_amdgcn_s_barrier()
; template <class Epi>
; __device__ __forceinline__ void gemm_phase(LAS unsigned char* lds, const Gemm g, const StaticOrder& S, const Epi& E) {
;     ...
;         if (wr == 0) PG8_BAR;
	s_add_i32 s34, s78, s89
	v_lshl_add_u64 v[120:121], v[214:215], 0, s[50:51]
	s_mov_b32 m0, s34
	s_nop 0
	global_load_lds_dwordx4 v[120:121], off
	s_add_i32 m0, s34, 0x2000
	s_add_u32 s34, s74, 0x80080
	v_lshl_add_u64 v[120:121], v[216:217], 0, s[50:51]
	s_addc_u32 s35, s75, 0
	s_add_i32 s74, s79, s89
	global_load_lds_dwordx4 v[120:121], off
	v_lshl_add_u64 v[120:121], s[34:35], 0, v[164:165]
	s_mov_b32 m0, s74
	s_nop 0
	global_load_lds_dwordx4 v[120:121], off
	v_lshl_add_u64 v[120:121], s[34:35], 0, v[168:169]
	s_add_i32 m0, s74, 0x2000
	s_nop 0
	global_load_lds_dwordx4 v[120:121], off
	v_lshl_add_u64 v[120:121], v[218:219], 0, s[50:51]
	s_mov_b32 m0, s95
	s_nop 0
	global_load_lds_dwordx4 v[120:121], off
	v_lshl_add_u64 v[120:121], v[234:235], 0, s[50:51]
	s_mov_b32 m0, s96
	s_nop 0
	global_load_lds_dwordx4 v[120:121], off
	ds_read_b128 v[182:185], v232 offset:49152
	ds_read_b128 v[186:189], v232 offset:50176
	ds_read_b128 v[190:193], v232 offset:51200
	ds_read_b128 v[194:197], v232 offset:52224
	ds_read_b128 v[198:201], v232 offset:53248
	ds_read_b128 v[202:205], v232 offset:54272
	ds_read_b128 v[206:209], v232 offset:55296
	ds_read_b128 v[210:213], v232 offset:56320
	s_waitcnt vmcnt(8)
	s_waitcnt lgkmcnt(0)
	s_barrier
	s_setprio 1
	s_waitcnt lgkmcnt(0)
	v_mfma_f32_16x16x32_bf16 v[52:55], v[130:133], v[182:185], v[52:55]
	v_mfma_f32_16x16x32_bf16 v[20:23], v[138:141], v[182:185], v[20:23]
	v_mfma_f32_16x16x32_bf16 v[44:47], v[130:133], v[190:193], v[44:47]
	v_mfma_f32_16x16x32_bf16 v[16:19], v[138:141], v[190:193], v[16:19]
	v_mfma_f32_16x16x32_bf16 v[36:39], v[130:133], v[198:201], v[36:39]
	v_mfma_f32_16x16x32_bf16 v[12:15], v[138:141], v[198:201], v[12:15]
	v_mfma_f32_16x16x32_bf16 v[76:79], v[130:133], v[206:209], v[76:79]
	v_mfma_f32_16x16x32_bf16 v[28:31], v[138:141], v[206:209], v[28:31]
	v_mfma_f32_16x16x32_bf16 v[52:55], v[134:137], v[186:189], v[52:55]
	v_mfma_f32_16x16x32_bf16 v[20:23], v[142:145], v[186:189], v[20:23]
	v_mfma_f32_16x16x32_bf16 v[44:47], v[134:137], v[194:197], v[44:47]
	v_mfma_f32_16x16x32_bf16 v[16:19], v[142:145], v[194:197], v[16:19]
	v_mfma_f32_16x16x32_bf16 v[36:39], v[134:137], v[202:205], v[36:39]
	v_mfma_f32_16x16x32_bf16 v[12:15], v[142:145], v[202:205], v[12:15]
	v_mfma_f32_16x16x32_bf16 v[76:79], v[134:137], v[210:213], v[76:79]
	v_mfma_f32_16x16x32_bf16 v[28:31], v[142:145], v[210:213], v[28:31]
	s_setprio 0
	s_setprio 1
	v_mfma_f32_16x16x32_bf16 v[48:51], v[146:149], v[182:185], v[48:51]
	v_mfma_f32_16x16x32_bf16 v[8:11], v[154:157], v[182:185], v[8:11]
	v_mfma_f32_16x16x32_bf16 v[40:43], v[146:149], v[190:193], v[40:43]
	v_mfma_f32_16x16x32_bf16 v[4:7], v[154:157], v[190:193], v[4:7]
	v_mfma_f32_16x16x32_bf16 v[32:35], v[146:149], v[198:201], v[32:35]
	v_mfma_f32_16x16x32_bf16 v[0:3], v[154:157], v[198:201], v[0:3]
	v_mfma_f32_16x16x32_bf16 v[72:75], v[146:149], v[206:209], v[72:75]
	v_mfma_f32_16x16x32_bf16 v[24:27], v[154:157], v[206:209], v[24:27]
	v_mfma_f32_16x16x32_bf16 v[48:51], v[150:153], v[186:189], v[48:51]
	v_mfma_f32_16x16x32_bf16 v[8:11], v[158:161], v[186:189], v[8:11]
	v_mfma_f32_16x16x32_bf16 v[40:43], v[150:153], v[194:197], v[40:43]
	v_mfma_f32_16x16x32_bf16 v[4:7], v[158:161], v[194:197], v[4:7]
	v_mfma_f32_16x16x32_bf16 v[32:35], v[150:153], v[202:205], v[32:35]
	v_mfma_f32_16x16x32_bf16 v[0:3], v[158:161], v[202:205], v[0:3]
	v_mfma_f32_16x16x32_bf16 v[72:75], v[150:153], v[210:213], v[72:75]
	v_mfma_f32_16x16x32_bf16 v[24:27], v[158:161], v[210:213], v[24:27]
	s_setprio 0
	s_barrier
	s_add_i32 s73, s73, 2
	s_add_u32 s10, s10, 0x100
	s_addc_u32 s11, s11, 0
	s_add_u32 s67, s67, 0x100
	s_addc_u32 s72, s72, 0
	s_cmp_gt_u32 s73, 29
	s_cbranch_scc0 .LBB0_896
	s_and_b64 vcc, exec, s[52:53]
	s_cbranch_vccz .LBB0_899
	s_barrier

.LBB0_1128:
	s_add_u32 s34, s26, 0xffea0080
	s_addc_u32 s35, s27, -1
	s_cmpk_eq_i32 s56, 0x54
	s_cselect_b32 s43, s1, s35
	s_cselect_b32 s42, s0, s34
	s_cselect_b32 s39, s25, s55
	s_cselect_b32 s38, s24, s54
	v_lshl_add_u64 v[150:151], s[26:27], 0, v[136:137]
	s_add_i32 m0, s40, 0xc000
	s_nop 0
	global_load_lds_dwordx4 v[150:151], off
	v_lshl_add_u64 v[150:151], s[26:27], 0, v[140:141]
	s_add_i32 m0, s40, 0xe000
	s_nop 0
	global_load_lds_dwordx4 v[150:151], off
	ds_read_b128 v[128:131], v158
	ds_read_b128 v[132:135], v158 offset:1024
	ds_read_b128 v[146:149], v158 offset:2048
	ds_read_b128 v[162:165], v158 offset:3072
	ds_read_b128 v[166:169], v159
	ds_read_b128 v[170:173], v159 offset:1024
	ds_read_b128 v[180:183], v159 offset:2048
	ds_read_b128 v[184:187], v159 offset:3072
	ds_read_b128 v[188:191], v160
	ds_read_b128 v[192:195], v160 offset:1024
	ds_read_b128 v[196:199], v160 offset:2048
	ds_read_b128 v[200:203], v160 offset:3072
	ds_read_b128 v[204:207], v160 offset:4096
	ds_read_b128 v[208:211], v160 offset:5120
	ds_read_b128 v[212:215], v160 offset:6144
	ds_read_b128 v[216:219], v160 offset:7168
	s_waitcnt vmcnt(8)
	s_waitcnt lgkmcnt(0)
	s_barrier
	s_setprio 1
	s_waitcnt lgkmcnt(0)
	v_mfma_f32_16x16x32_bf16 v[76:79], v[128:131], v[188:191], v[76:79]
	v_mfma_f32_16x16x32_bf16 v[72:75], v[146:149], v[188:191], v[72:75]
	v_mfma_f32_16x16x32_bf16 v[124:127], v[128:131], v[196:199], v[124:127]
	v_mfma_f32_16x16x32_bf16 v[120:123], v[146:149], v[196:199], v[120:123]
	v_mfma_f32_16x16x32_bf16 v[116:119], v[128:131], v[204:207], v[116:119]
	v_mfma_f32_16x16x32_bf16 v[112:115], v[146:149], v[204:207], v[112:115]
	v_mfma_f32_16x16x32_bf16 v[96:99], v[128:131], v[212:215], v[96:99]
	v_mfma_f32_16x16x32_bf16 v[92:95], v[146:149], v[212:215], v[92:95]
	v_mfma_f32_16x16x32_bf16 v[76:79], v[132:135], v[192:195], v[76:79]
	v_mfma_f32_16x16x32_bf16 v[72:75], v[162:165], v[192:195], v[72:75]
	v_mfma_f32_16x16x32_bf16 v[124:127], v[132:135], v[200:203], v[124:127]
	v_mfma_f32_16x16x32_bf16 v[120:123], v[162:165], v[200:203], v[120:123]
	v_mfma_f32_16x16x32_bf16 v[116:119], v[132:135], v[208:211], v[116:119]
	v_mfma_f32_16x16x32_bf16 v[112:115], v[162:165], v[208:211], v[112:115]
	v_mfma_f32_16x16x32_bf16 v[96:99], v[132:135], v[216:219], v[96:99]
	v_mfma_f32_16x16x32_bf16 v[92:95], v[162:165], v[216:219], v[92:95]
	s_setprio 0
	s_setprio 1
	v_mfma_f32_16x16x32_bf16 v[68:71], v[166:169], v[188:191], v[68:71]
	v_mfma_f32_16x16x32_bf16 v[64:67], v[180:183], v[188:191], v[64:67]
	v_mfma_f32_16x16x32_bf16 v[108:111], v[166:169], v[196:199], v[108:111]
	v_mfma_f32_16x16x32_bf16 v[104:107], v[180:183], v[196:199], v[104:107]
	v_mfma_f32_16x16x32_bf16 v[100:103], v[166:169], v[204:207], v[100:103]
	v_mfma_f32_16x16x32_bf16 v[88:91], v[180:183], v[204:207], v[88:91]
	v_mfma_f32_16x16x32_bf16 v[84:87], v[166:169], v[212:215], v[84:87]
	v_mfma_f32_16x16x32_bf16 v[80:83], v[180:183], v[212:215], v[80:83]
	v_mfma_f32_16x16x32_bf16 v[68:71], v[170:173], v[192:195], v[68:71]
	v_mfma_f32_16x16x32_bf16 v[64:67], v[184:187], v[192:195], v[64:67]
	v_mfma_f32_16x16x32_bf16 v[108:111], v[170:173], v[200:203], v[108:111]
	v_mfma_f32_16x16x32_bf16 v[104:107], v[184:187], v[200:203], v[104:107]
	v_mfma_f32_16x16x32_bf16 v[100:103], v[170:173], v[208:211], v[100:103]
	v_mfma_f32_16x16x32_bf16 v[88:91], v[184:187], v[208:211], v[88:91]
	v_mfma_f32_16x16x32_bf16 v[84:87], v[170:173], v[216:219], v[84:87]
	v_mfma_f32_16x16x32_bf16 v[80:83], v[184:187], v[216:219], v[80:83]
	s_setprio 0
	s_barrier
	s_add_i32 s34, s8, s33
	v_lshl_add_u64 v[150:151], s[38:39], 0, v[138:139]
	s_mov_b32 m0, s34
	s_nop 0
	global_load_lds_dwordx4 v[150:151], off
	s_add_i32 m0, s34, 0x2000
	s_add_u32 s34, s38, 0x160000
	v_lshl_add_u64 v[174:175], s[38:39], 0, v[142:143]
	s_addc_u32 s35, s39, 0
	s_add_i32 s57, s49, s33
	global_load_lds_dwordx4 v[174:175], off
	v_lshl_add_u64 v[222:223], s[34:35], 0, v[138:139]
	s_mov_b32 m0, s57
	v_lshl_add_u64 v[224:225], s[42:43], 0, v[140:141]
	global_load_lds_dwordx4 v[222:223], off
	v_lshl_add_u64 v[222:223], s[34:35], 0, v[142:143]
	s_add_i32 m0, s57, 0x2000
	s_nop 0
	global_load_lds_dwordx4 v[222:223], off
	v_lshl_add_u64 v[222:223], s[42:43], 0, v[136:137]
	s_mov_b32 m0, s40
	s_nop 0
	global_load_lds_dwordx4 v[222:223], off
	s_mov_b32 m0, s41
	s_nop 0
	global_load_lds_dwordx4 v[224:225], off
	ds_read_b128 v[188:191], v160 offset:16384
	ds_read_b128 v[192:195], v160 offset:17408
	ds_read_b128 v[196:199], v160 offset:18432
	ds_read_b128 v[200:203], v160 offset:19456
	ds_read_b128 v[204:207], v160 offset:20480
	ds_read_b128 v[208:211], v160 offset:21504
	ds_read_b128 v[212:215], v160 offset:22528
	ds_read_b128 v[216:219], v160 offset:23552
	s_waitcnt vmcnt(8)
	s_waitcnt lgkmcnt(0)
	s_barrier
	s_setprio 1
	s_waitcnt lgkmcnt(0)
	v_mfma_f32_16x16x32_bf16 v[60:63], v[128:131], v[188:191], v[60:63]
	v_mfma_f32_16x16x32_bf16 v[56:59], v[146:149], v[188:191], v[56:59]
	v_mfma_f32_16x16x32_bf16 v[48:51], v[128:131], v[196:199], v[48:51]
	v_mfma_f32_16x16x32_bf16 v[40:43], v[146:149], v[196:199], v[40:43]
	v_mfma_f32_16x16x32_bf16 v[36:39], v[128:131], v[204:207], v[36:39]
	v_mfma_f32_16x16x32_bf16 v[28:31], v[146:149], v[204:207], v[28:31]
	v_mfma_f32_16x16x32_bf16 v[20:23], v[128:131], v[212:215], v[20:23]
	v_mfma_f32_16x16x32_bf16 v[12:15], v[146:149], v[212:215], v[12:15]
	v_mfma_f32_16x16x32_bf16 v[60:63], v[132:135], v[192:195], v[60:63]
	v_mfma_f32_16x16x32_bf16 v[56:59], v[162:165], v[192:195], v[56:59]
	v_mfma_f32_16x16x32_bf16 v[48:51], v[132:135], v[200:203], v[48:51]
	v_mfma_f32_16x16x32_bf16 v[40:43], v[162:165], v[200:203], v[40:43]
	v_mfma_f32_16x16x32_bf16 v[36:39], v[132:135], v[208:211], v[36:39]
	v_mfma_f32_16x16x32_bf16 v[28:31], v[162:165], v[208:211], v[28:31]
	v_mfma_f32_16x16x32_bf16 v[20:23], v[132:135], v[216:219], v[20:23]
	v_mfma_f32_16x16x32_bf16 v[12:15], v[162:165], v[216:219], v[12:15]
	s_setprio 0
	s_setprio 1
	v_mfma_f32_16x16x32_bf16 v[52:55], v[166:169], v[188:191], v[52:55]
	v_mfma_f32_16x16x32_bf16 v[44:47], v[180:183], v[188:191], v[44:47]
	v_mfma_f32_16x16x32_bf16 v[32:35], v[166:169], v[196:199], v[32:35]
	v_mfma_f32_16x16x32_bf16 v[24:27], v[180:183], v[196:199], v[24:27]
	v_mfma_f32_16x16x32_bf16 v[16:19], v[166:169], v[204:207], v[16:19]
	v_mfma_f32_16x16x32_bf16 v[8:11], v[180:183], v[204:207], v[8:11]
	v_mfma_f32_16x16x32_bf16 v[4:7], v[166:169], v[212:215], v[4:7]
	v_mfma_f32_16x16x32_bf16 v[0:3], v[180:183], v[212:215], v[0:3]
	v_mfma_f32_16x16x32_bf16 v[52:55], v[170:173], v[192:195], v[52:55]
	v_mfma_f32_16x16x32_bf16 v[44:47], v[184:187], v[192:195], v[44:47]
	v_mfma_f32_16x16x32_bf16 v[32:35], v[170:173], v[200:203], v[32:35]
	v_mfma_f32_16x16x32_bf16 v[24:27], v[184:187], v[200:203], v[24:27]
	v_mfma_f32_16x16x32_bf16 v[16:19], v[170:173], v[208:211], v[16:19]
	v_mfma_f32_16x16x32_bf16 v[8:11], v[184:187], v[208:211], v[8:11]
	v_mfma_f32_16x16x32_bf16 v[4:7], v[170:173], v[216:219], v[4:7]
	v_mfma_f32_16x16x32_bf16 v[0:3], v[184:187], v[216:219], v[0:3]
	s_setprio 0
	s_barrier
	s_add_i32 s57, 0, 0x18000
	s_add_i32 s58, 0, 0x1c000
	s_add_u32 s34, s42, 0x160000
	s_addc_u32 s35, s43, 0
	s_mov_b32 m0, s44
	v_lshl_add_u64 v[226:227], s[34:35], 0, v[136:137]
	global_load_lds_dwordx4 v[226:227], off
	v_lshl_add_u64 v[226:227], s[34:35], 0, v[140:141]
	s_mov_b32 m0, s45
	s_nop 0
	global_load_lds_dwordx4 v[226:227], off
	v_add_u32_e32 v161, s57, v153
	ds_read_b128 v[128:131], v161
	ds_read_b128 v[132:135], v161 offset:1024
	ds_read_b128 v[146:149], v161 offset:2048
	ds_read_b128 v[162:165], v161 offset:3072
	v_add_u32_e32 v161, s58, v153
	ds_read_b128 v[166:169], v161
	ds_read_b128 v[170:173], v161 offset:1024
	ds_read_b128 v[180:183], v161 offset:2048
	ds_read_b128 v[184:187], v161 offset:3072
	ds_read_b128 v[188:191], v160 offset:32768
	ds_read_b128 v[192:195], v160 offset:33792
	ds_read_b128 v[196:199], v160 offset:34816
	ds_read_b128 v[200:203], v160 offset:35840
	ds_read_b128 v[204:207], v160 offset:36864
	ds_read_b128 v[208:211], v160 offset:37888
	ds_read_b128 v[212:215], v160 offset:38912
	ds_read_b128 v[216:219], v160 offset:39936
	s_waitcnt vmcnt(8)
	s_waitcnt lgkmcnt(0)
	s_barrier
	s_setprio 1
	s_waitcnt lgkmcnt(0)
	v_mfma_f32_16x16x32_bf16 v[76:79], v[128:131], v[188:191], v[76:79]
	v_mfma_f32_16x16x32_bf16 v[72:75], v[146:149], v[188:191], v[72:75]
	v_mfma_f32_16x16x32_bf16 v[124:127], v[128:131], v[196:199], v[124:127]
	v_mfma_f32_16x16x32_bf16 v[120:123], v[146:149], v[196:199], v[120:123]
	v_mfma_f32_16x16x32_bf16 v[116:119], v[128:131], v[204:207], v[116:119]
	v_mfma_f32_16x16x32_bf16 v[112:115], v[146:149], v[204:207], v[112:115]
	v_mfma_f32_16x16x32_bf16 v[96:99], v[128:131], v[212:215], v[96:99]
	v_mfma_f32_16x16x32_bf16 v[92:95], v[146:149], v[212:215], v[92:95]
	v_mfma_f32_16x16x32_bf16 v[76:79], v[132:135], v[192:195], v[76:79]
	v_mfma_f32_16x16x32_bf16 v[72:75], v[162:165], v[192:195], v[72:75]
	v_mfma_f32_16x16x32_bf16 v[124:127], v[132:135], v[200:203], v[124:127]
	v_mfma_f32_16x16x32_bf16 v[120:123], v[162:165], v[200:203], v[120:123]
	v_mfma_f32_16x16x32_bf16 v[116:119], v[132:135], v[208:211], v[116:119]
	v_mfma_f32_16x16x32_bf16 v[112:115], v[162:165], v[208:211], v[112:115]
	v_mfma_f32_16x16x32_bf16 v[96:99], v[132:135], v[216:219], v[96:99]
	v_mfma_f32_16x16x32_bf16 v[92:95], v[162:165], v[216:219], v[92:95]
	s_setprio 0
	s_setprio 1
	v_mfma_f32_16x16x32_bf16 v[68:71], v[166:169], v[188:191], v[68:71]
	v_mfma_f32_16x16x32_bf16 v[64:67], v[180:183], v[188:191], v[64:67]
	v_mfma_f32_16x16x32_bf16 v[108:111], v[166:169], v[196:199], v[108:111]
	v_mfma_f32_16x16x32_bf16 v[104:107], v[180:183], v[196:199], v[104:107]
	v_mfma_f32_16x16x32_bf16 v[100:103], v[166:169], v[204:207], v[100:103]
	v_mfma_f32_16x16x32_bf16 v[88:91], v[180:183], v[204:207], v[88:91]
	v_mfma_f32_16x16x32_bf16 v[84:87], v[166:169], v[212:215], v[84:87]
	v_mfma_f32_16x16x32_bf16 v[80:83], v[180:183], v[212:215], v[80:83]
	v_mfma_f32_16x16x32_bf16 v[68:71], v[170:173], v[192:195], v[68:71]
	v_mfma_f32_16x16x32_bf16 v[64:67], v[184:187], v[192:195], v[64:67]
	v_mfma_f32_16x16x32_bf16 v[108:111], v[170:173], v[200:203], v[108:111]
	v_mfma_f32_16x16x32_bf16 v[104:107], v[184:187], v[200:203], v[104:107]
	v_mfma_f32_16x16x32_bf16 v[100:103], v[170:173], v[208:211], v[100:103]
	v_mfma_f32_16x16x32_bf16 v[88:91], v[184:187], v[208:211], v[88:91]
	v_mfma_f32_16x16x32_bf16 v[84:87], v[170:173], v[216:219], v[84:87]
	v_mfma_f32_16x16x32_bf16 v[80:83], v[184:187], v[216:219], v[80:83]
	s_setprio 0
	s_barrier
	s_add_i32 s34, s57, s33
	v_lshl_add_u64 v[150:151], v[150:151], 0, s[14:15]
	s_mov_b32 m0, s34
	s_nop 0
	global_load_lds_dwordx4 v[150:151], off
	s_add_i32 m0, s34, 0x2000
	s_add_u32 s34, s38, 0x160080
	v_lshl_add_u64 v[150:151], v[174:175], 0, s[14:15]
	s_addc_u32 s35, s39, 0
	s_add_i32 s38, s58, s33
	global_load_lds_dwordx4 v[150:151], off
	v_lshl_add_u64 v[150:151], s[34:35], 0, v[138:139]
	s_mov_b32 m0, s38
	s_nop 0
	global_load_lds_dwordx4 v[150:151], off
	v_lshl_add_u64 v[150:151], s[34:35], 0, v[142:143]
	s_add_i32 m0, s38, 0x2000
	s_nop 0
	global_load_lds_dwordx4 v[150:151], off
	v_lshl_add_u64 v[150:151], v[222:223], 0, s[14:15]
	s_mov_b32 m0, s46
	s_nop 0
	global_load_lds_dwordx4 v[150:151], off
	v_lshl_add_u64 v[150:151], v[224:225], 0, s[14:15]
	s_mov_b32 m0, s47
	s_nop 0
	global_load_lds_dwordx4 v[150:151], off
	ds_read_b128 v[188:191], v160 offset:49152
	ds_read_b128 v[192:195], v160 offset:50176
	ds_read_b128 v[196:199], v160 offset:51200
	ds_read_b128 v[200:203], v160 offset:52224
	ds_read_b128 v[204:207], v160 offset:53248
	ds_read_b128 v[208:211], v160 offset:54272
	ds_read_b128 v[212:215], v160 offset:55296
	ds_read_b128 v[216:219], v160 offset:56320
	s_waitcnt vmcnt(8)
	s_waitcnt lgkmcnt(0)
	s_barrier
	s_setprio 1
	s_waitcnt lgkmcnt(0)
	v_mfma_f32_16x16x32_bf16 v[60:63], v[128:131], v[188:191], v[60:63]
	v_mfma_f32_16x16x32_bf16 v[56:59], v[146:149], v[188:191], v[56:59]
	v_mfma_f32_16x16x32_bf16 v[48:51], v[128:131], v[196:199], v[48:51]
	v_mfma_f32_16x16x32_bf16 v[40:43], v[146:149], v[196:199], v[40:43]
	v_mfma_f32_16x16x32_bf16 v[36:39], v[128:131], v[204:207], v[36:39]
	v_mfma_f32_16x16x32_bf16 v[28:31], v[146:149], v[204:207], v[28:31]
	v_mfma_f32_16x16x32_bf16 v[20:23], v[128:131], v[212:215], v[20:23]
	v_mfma_f32_16x16x32_bf16 v[12:15], v[146:149], v[212:215], v[12:15]
	v_mfma_f32_16x16x32_bf16 v[60:63], v[132:135], v[192:195], v[60:63]
	v_mfma_f32_16x16x32_bf16 v[56:59], v[162:165], v[192:195], v[56:59]
	v_mfma_f32_16x16x32_bf16 v[48:51], v[132:135], v[200:203], v[48:51]
	v_mfma_f32_16x16x32_bf16 v[40:43], v[162:165], v[200:203], v[40:43]
	v_mfma_f32_16x16x32_bf16 v[36:39], v[132:135], v[208:211], v[36:39]
	v_mfma_f32_16x16x32_bf16 v[28:31], v[162:165], v[208:211], v[28:31]
	v_mfma_f32_16x16x32_bf16 v[20:23], v[132:135], v[216:219], v[20:23]
	v_mfma_f32_16x16x32_bf16 v[12:15], v[162:165], v[216:219], v[12:15]
	s_setprio 0
	s_setprio 1
	v_mfma_f32_16x16x32_bf16 v[52:55], v[166:169], v[188:191], v[52:55]
	v_mfma_f32_16x16x32_bf16 v[44:47], v[180:183], v[188:191], v[44:47]
	v_mfma_f32_16x16x32_bf16 v[32:35], v[166:169], v[196:199], v[32:35]
	v_mfma_f32_16x16x32_bf16 v[24:27], v[180:183], v[196:199], v[24:27]
	v_mfma_f32_16x16x32_bf16 v[16:19], v[166:169], v[204:207], v[16:19]
	v_mfma_f32_16x16x32_bf16 v[8:11], v[180:183], v[204:207], v[8:11]
	v_mfma_f32_16x16x32_bf16 v[4:7], v[166:169], v[212:215], v[4:7]
	v_mfma_f32_16x16x32_bf16 v[0:3], v[180:183], v[212:215], v[0:3]
	v_mfma_f32_16x16x32_bf16 v[52:55], v[170:173], v[192:195], v[52:55]
	v_mfma_f32_16x16x32_bf16 v[44:47], v[184:187], v[192:195], v[44:47]
	v_mfma_f32_16x16x32_bf16 v[32:35], v[170:173], v[200:203], v[32:35]
	v_mfma_f32_16x16x32_bf16 v[24:27], v[184:187], v[200:203], v[24:27]
	v_mfma_f32_16x16x32_bf16 v[16:19], v[170:173], v[208:211], v[16:19]
	v_mfma_f32_16x16x32_bf16 v[8:11], v[184:187], v[208:211], v[8:11]
	v_mfma_f32_16x16x32_bf16 v[4:7], v[170:173], v[216:219], v[4:7]
	v_mfma_f32_16x16x32_bf16 v[0:3], v[184:187], v[216:219], v[0:3]
	s_setprio 0
	s_barrier
	s_add_i32 s56, s56, 2
	s_add_u32 s26, s26, 0x100
	s_addc_u32 s27, s27, 0
	s_add_u32 s54, s54, 0x100
	s_addc_u32 s55, s55, 0
	s_cmpk_gt_u32 s56, 0x55
	s_cbranch_scc0 .LBB0_1128
	s_and_b64 vcc, exec, s[22:23]
	s_cbranch_vccz .LBB0_1131
	s_barrier
